# v2 + GEMM K-loops: per-segment s_setprio flips deleted, one static s_setprio 1 for waves 4-7 at each GEMM phase entry
# speedup vs baseline: 1.0055x; 1.0029x over previous
.LBB0_210:
	s_and_b32 s3, s3, 3
	s_lshl_b32 s12, s2, 13
	s_lshl_b32 s13, s3, 9
	s_add_u32 s4, s88, 0x188800
	s_addc_u32 s5, s89, 0
	s_add_i32 m0, s68, 0x18000
	v_lshl_add_u64 v[8:9], s[4:5], 0, v[132:133]
	s_waitcnt vmcnt(2)
	s_barrier
	global_load_lds_dwordx4 v[8:9], off
	v_lshl_add_u64 v[8:9], s[4:5], 0, v[136:137]
	s_add_i32 m0, s68, 0x1a000
	s_mov_b64 s[52:53], 0x80
	s_add_i32 s8, s68, 0x8000
	s_add_i32 s9, s68, 0xa000
	global_load_lds_dwordx4 v[8:9], off
	v_lshl_add_u64 v[2:3], v[2:3], 0, s[52:53]
	s_mov_b32 m0, s8
	s_add_u32 s4, s88, 0x189000
	global_load_lds_dwordx4 v[2:3], off
	v_lshl_add_u64 v[2:3], v[4:5], 0, s[52:53]
	s_mov_b32 m0, s9
	s_addc_u32 s5, s89, 0
	global_load_lds_dwordx4 v[2:3], off
	s_add_i32 m0, s68, 0x1c000
	v_lshl_add_u64 v[2:3], s[4:5], 0, v[132:133]
	global_load_lds_dwordx4 v[2:3], off
	v_lshl_add_u64 v[2:3], s[4:5], 0, v[136:137]
	s_add_i32 m0, s68, 0x1e000
	v_and_b32_e32 v1, 15, v6
	global_load_lds_dwordx4 v[2:3], off
	v_bfe_u32 v2, v6, 4, 2
	v_lshlrev_b32_e32 v3, 4, v2
	v_lshlrev_b32_e32 v4, 2, v6
	v_lshl_or_b32 v3, v1, 6, v3
	v_and_b32_e32 v4, 32, v4
	v_lshlrev_b32_e32 v2, 11, v2
	v_lshlrev_b32_e32 v1, 4, v1
	s_cmpk_lt_u32 s0, 0x100
	v_bitop3_b32 v3, v3, s12, v4 bitop3:0xde
	v_or3_b32 v1, s13, v1, v2
	s_cselect_b64 s[66:67], -1, 0
	v_bfe_u32 v2, v6, 2, 4
	v_and_b32_e32 v4, 3, v6
	s_ashr_i32 s0, s92, 31
	v_lshl_or_b32 v143, s2, 6, v2
	v_lshlrev_b32_e32 v2, 3, v4
	v_writelane_b32 v249, s0, 58
	v_lshl_or_b32 v144, s3, 5, v2
	v_readlane_b32 s2, v249, 2
	s_mov_b32 s0, s2
	s_ashr_i32 s2, s2, 31
	v_readlane_b32 s3, v249, 3
	v_writelane_b32 v249, s2, 60
	s_and_b32 s2, s0, 7
	s_waitcnt vmcnt(6)
	v_writelane_b32 v249, s2, 61
	s_bfe_u32 s2, s0, 0x30003
	v_and_b32_e32 v5, 60, v6
	v_writelane_b32 v249, s2, 62
	s_ashr_i32 s0, s0, 6
	v_lshl_or_b32 v142, v4, 6, v5
	v_writelane_b32 v249, s0, 63
	v_mov_b32_e32 v146, s1
	s_add_i32 s0, 0, 0x10000
	s_add_i32 s1, 0, 0x14000
	v_add_u32_e32 v145, 0, v3
	s_movk_i32 s72, 0x6080
	v_mov_b64_e32 v[138:139], 0x8ff
	s_barrier
	v_readfirstlane_b32 s98, v0
	s_nop 3
	s_and_b32 s98, s98, 0x3ff
	s_cmp_ge_u32 s98, 0x100
	s_cbranch_scc0 .Lprio_done0
	s_setprio 1
.Lprio_done0:
	s_branch .LBB0_213
.LBB0_211:
	s_mov_b64 s[2:3], 0

.LBB0_249:
	s_lshl_b32 s2, s87, 7
	s_add_u32 s12, s84, s2
	s_addc_u32 s13, s85, 0
	s_add_u32 s4, s12, 0x100
	s_addc_u32 s5, s13, 0
	s_and_b64 s[2:3], s[92:93], exec
	v_add_u32_e32 v140, s0, v1
	s_mul_i32 s2, s87, 0x188800
	ds_read_b128 v[148:151], v140
	ds_read_b128 v[152:155], v140 offset:256
	ds_read_b128 v[156:159], v140 offset:8192
	ds_read_b128 v[160:163], v140 offset:8448
	v_add_u32_e32 v140, s1, v1
	s_cselect_b32 s5, s5, s81
	s_cselect_b32 s4, s4, s80
	s_add_u32 s2, s88, s2
	ds_read_b128 v[164:167], v140
	ds_read_b128 v[168:171], v140 offset:256
	ds_read_b128 v[172:175], v140 offset:8192
	ds_read_b128 v[176:179], v140 offset:8448
	s_addc_u32 s3, s89, 0
	s_add_u32 s20, s2, 0x311000
	s_addc_u32 s21, s3, 0
	s_and_b64 s[2:3], s[92:93], exec
	s_cselect_b32 s92, s20, s86
	s_cselect_b32 s93, s21, s75
	s_add_u32 s94, s92, 0x188800
	s_addc_u32 s95, s93, 0
	s_add_u32 s2, s12, 0x104080
	s_addc_u32 s3, s13, 0
	v_lshl_add_u64 v[140:141], s[2:3], 0, v[130:131]
	s_add_i32 m0, s68, 0xc000
	ds_read_b128 v[180:183], v145
	ds_read_b128 v[184:187], v145 offset:1024
	ds_read_b128 v[188:191], v145 offset:2048
	ds_read_b128 v[192:195], v145 offset:3072
	ds_read_b128 v[196:199], v145 offset:4096
	ds_read_b128 v[200:203], v145 offset:5120
	ds_read_b128 v[204:207], v145 offset:6144
	ds_read_b128 v[208:211], v145 offset:7168
	global_load_lds_dwordx4 v[140:141], off
	v_lshl_add_u64 v[140:141], s[2:3], 0, v[134:135]
	s_add_i32 m0, s68, 0xe000
	s_nop 0
	global_load_lds_dwordx4 v[140:141], off
	s_waitcnt vmcnt(8)
	s_waitcnt lgkmcnt(0)
	s_barrier
	s_waitcnt lgkmcnt(0)
	v_mfma_f32_16x16x32_bf16 v[126:129], v[148:151], v[180:183], v[126:129]
	v_mfma_f32_16x16x32_bf16 v[122:125], v[152:155], v[180:183], v[122:125]
	v_mfma_f32_16x16x32_bf16 v[118:121], v[148:151], v[188:191], v[118:121]
	v_mfma_f32_16x16x32_bf16 v[110:113], v[152:155], v[188:191], v[110:113]
	v_mfma_f32_16x16x32_bf16 v[102:105], v[148:151], v[196:199], v[102:105]
	v_mfma_f32_16x16x32_bf16 v[94:97], v[152:155], v[196:199], v[94:97]
	v_mfma_f32_16x16x32_bf16 v[86:89], v[148:151], v[204:207], v[86:89]
	v_mfma_f32_16x16x32_bf16 v[78:81], v[152:155], v[204:207], v[78:81]
	v_mfma_f32_16x16x32_bf16 v[126:129], v[156:159], v[184:187], v[126:129]
	v_mfma_f32_16x16x32_bf16 v[122:125], v[160:163], v[184:187], v[122:125]
	v_mfma_f32_16x16x32_bf16 v[118:121], v[156:159], v[192:195], v[118:121]
	v_mfma_f32_16x16x32_bf16 v[110:113], v[160:163], v[192:195], v[110:113]
	v_mfma_f32_16x16x32_bf16 v[102:105], v[156:159], v[200:203], v[102:105]
	v_mfma_f32_16x16x32_bf16 v[94:97], v[160:163], v[200:203], v[94:97]
	v_mfma_f32_16x16x32_bf16 v[86:89], v[156:159], v[208:211], v[86:89]
	v_mfma_f32_16x16x32_bf16 v[78:81], v[160:163], v[208:211], v[78:81]
	v_mfma_f32_16x16x32_bf16 v[114:117], v[164:167], v[180:183], v[114:117]
	v_mfma_f32_16x16x32_bf16 v[106:109], v[168:171], v[180:183], v[106:109]
	v_mfma_f32_16x16x32_bf16 v[98:101], v[164:167], v[188:191], v[98:101]
	v_mfma_f32_16x16x32_bf16 v[90:93], v[168:171], v[188:191], v[90:93]
	v_mfma_f32_16x16x32_bf16 v[82:85], v[164:167], v[196:199], v[82:85]
	v_mfma_f32_16x16x32_bf16 v[74:77], v[168:171], v[196:199], v[74:77]
	v_mfma_f32_16x16x32_bf16 v[70:73], v[164:167], v[204:207], v[70:73]
	v_mfma_f32_16x16x32_bf16 v[66:69], v[168:171], v[204:207], v[66:69]
	v_mfma_f32_16x16x32_bf16 v[114:117], v[172:175], v[184:187], v[114:117]
	v_mfma_f32_16x16x32_bf16 v[106:109], v[176:179], v[184:187], v[106:109]
	v_mfma_f32_16x16x32_bf16 v[98:101], v[172:175], v[192:195], v[98:101]
	v_mfma_f32_16x16x32_bf16 v[90:93], v[176:179], v[192:195], v[90:93]
	v_mfma_f32_16x16x32_bf16 v[82:85], v[172:175], v[200:203], v[82:85]
	v_mfma_f32_16x16x32_bf16 v[74:77], v[176:179], v[200:203], v[74:77]
	v_mfma_f32_16x16x32_bf16 v[70:73], v[172:175], v[208:211], v[70:73]
	v_mfma_f32_16x16x32_bf16 v[66:69], v[176:179], v[208:211], v[66:69]
	s_barrier
	s_add_i32 s2, s0, s15
	v_lshl_add_u64 v[140:141], s[92:93], 0, v[132:133]
	s_mov_b32 m0, s2
	ds_read_b128 v[180:183], v145 offset:16384
	ds_read_b128 v[184:187], v145 offset:17408
	ds_read_b128 v[188:191], v145 offset:18432
	ds_read_b128 v[192:195], v145 offset:19456
	ds_read_b128 v[196:199], v145 offset:20480
	ds_read_b128 v[200:203], v145 offset:21504
	ds_read_b128 v[204:207], v145 offset:22528
	ds_read_b128 v[208:211], v145 offset:23552
	global_load_lds_dwordx4 v[140:141], off
	v_lshl_add_u64 v[212:213], s[92:93], 0, v[136:137]
	s_add_i32 m0, s2, 0x2000
	s_add_i32 s2, s1, s15
	global_load_lds_dwordx4 v[212:213], off
	v_lshl_add_u64 v[140:141], v[140:141], 0, s[10:11]
	s_mov_b32 m0, s2
	s_nop 0
	global_load_lds_dwordx4 v[140:141], off
	v_lshl_add_u64 v[140:141], v[212:213], 0, s[10:11]
	s_add_i32 m0, s2, 0x2000
	v_lshl_add_u64 v[212:213], s[4:5], 0, v[134:135]
	global_load_lds_dwordx4 v[140:141], off
	v_lshl_add_u64 v[140:141], s[4:5], 0, v[130:131]
	s_mov_b32 m0, s68
	s_nop 0
	global_load_lds_dwordx4 v[140:141], off
	s_mov_b32 m0, s69
	s_nop 0
	global_load_lds_dwordx4 v[212:213], off
	s_waitcnt vmcnt(8)
	s_waitcnt lgkmcnt(0)
	s_barrier
	s_waitcnt lgkmcnt(0)
	v_mfma_f32_16x16x32_bf16 v[62:65], v[148:151], v[180:183], v[62:65]
	v_mfma_f32_16x16x32_bf16 v[58:61], v[152:155], v[180:183], v[58:61]
	v_mfma_f32_16x16x32_bf16 v[54:57], v[148:151], v[188:191], v[54:57]
	v_mfma_f32_16x16x32_bf16 v[46:49], v[152:155], v[188:191], v[46:49]
	v_mfma_f32_16x16x32_bf16 v[38:41], v[148:151], v[196:199], v[38:41]
	v_mfma_f32_16x16x32_bf16 v[30:33], v[152:155], v[196:199], v[30:33]
	v_mfma_f32_16x16x32_bf16 v[22:25], v[148:151], v[204:207], v[22:25]
	v_mfma_f32_16x16x32_bf16 v[14:17], v[152:155], v[204:207], v[14:17]
	v_mfma_f32_16x16x32_bf16 v[62:65], v[156:159], v[184:187], v[62:65]
	v_mfma_f32_16x16x32_bf16 v[58:61], v[160:163], v[184:187], v[58:61]
	v_mfma_f32_16x16x32_bf16 v[54:57], v[156:159], v[192:195], v[54:57]
	v_mfma_f32_16x16x32_bf16 v[46:49], v[160:163], v[192:195], v[46:49]
	v_mfma_f32_16x16x32_bf16 v[38:41], v[156:159], v[200:203], v[38:41]
	v_mfma_f32_16x16x32_bf16 v[30:33], v[160:163], v[200:203], v[30:33]
	v_mfma_f32_16x16x32_bf16 v[22:25], v[156:159], v[208:211], v[22:25]
	v_mfma_f32_16x16x32_bf16 v[14:17], v[160:163], v[208:211], v[14:17]
	v_mfma_f32_16x16x32_bf16 v[50:53], v[164:167], v[180:183], v[50:53]
	v_mfma_f32_16x16x32_bf16 v[42:45], v[168:171], v[180:183], v[42:45]
	v_mfma_f32_16x16x32_bf16 v[34:37], v[164:167], v[188:191], v[34:37]
	v_mfma_f32_16x16x32_bf16 v[26:29], v[168:171], v[188:191], v[26:29]
	v_mfma_f32_16x16x32_bf16 v[18:21], v[164:167], v[196:199], v[18:21]
	v_mfma_f32_16x16x32_bf16 v[10:13], v[168:171], v[196:199], v[10:13]
	v_mfma_f32_16x16x32_bf16 v[6:9], v[164:167], v[204:207], v[6:9]
	v_mfma_f32_16x16x32_bf16 v[2:5], v[168:171], v[204:207], v[2:5]
	v_mfma_f32_16x16x32_bf16 v[50:53], v[172:175], v[184:187], v[50:53]
	v_mfma_f32_16x16x32_bf16 v[42:45], v[176:179], v[184:187], v[42:45]
	v_mfma_f32_16x16x32_bf16 v[34:37], v[172:175], v[192:195], v[34:37]
	v_mfma_f32_16x16x32_bf16 v[26:29], v[176:179], v[192:195], v[26:29]
	v_mfma_f32_16x16x32_bf16 v[18:21], v[172:175], v[200:203], v[18:21]
	v_mfma_f32_16x16x32_bf16 v[10:13], v[176:179], v[200:203], v[10:13]
	v_mfma_f32_16x16x32_bf16 v[6:9], v[172:175], v[208:211], v[6:9]
	v_mfma_f32_16x16x32_bf16 v[2:5], v[176:179], v[208:211], v[2:5]
	s_barrier
	s_add_i32 s12, 0, 0x18000
	v_add_u32_e32 v147, s12, v1
	s_add_i32 s13, 0, 0x1c000
	ds_read_b128 v[148:151], v147
	ds_read_b128 v[152:155], v147 offset:256
	ds_read_b128 v[156:159], v147 offset:8192
	ds_read_b128 v[160:163], v147 offset:8448
	v_add_u32_e32 v147, s13, v1
	ds_read_b128 v[164:167], v147
	ds_read_b128 v[168:171], v147 offset:256
	ds_read_b128 v[172:175], v147 offset:8192
	ds_read_b128 v[176:179], v147 offset:8448
	s_add_u32 s2, s4, 0x104000
	s_addc_u32 s3, s5, 0
	s_mov_b32 m0, s70
	v_lshl_add_u64 v[214:215], s[2:3], 0, v[130:131]
	ds_read_b128 v[180:183], v145 offset:32768
	ds_read_b128 v[184:187], v145 offset:33792
	ds_read_b128 v[188:191], v145 offset:34816
	ds_read_b128 v[192:195], v145 offset:35840
	ds_read_b128 v[196:199], v145 offset:36864
	ds_read_b128 v[200:203], v145 offset:37888
	ds_read_b128 v[204:207], v145 offset:38912
	ds_read_b128 v[208:211], v145 offset:39936
	global_load_lds_dwordx4 v[214:215], off
	v_lshl_add_u64 v[214:215], s[2:3], 0, v[134:135]
	s_mov_b32 m0, s71
	s_nop 0
	global_load_lds_dwordx4 v[214:215], off
	s_waitcnt vmcnt(8)
	s_waitcnt lgkmcnt(0)
	s_barrier
	s_waitcnt lgkmcnt(0)
	v_mfma_f32_16x16x32_bf16 v[126:129], v[148:151], v[180:183], v[126:129]
	v_mfma_f32_16x16x32_bf16 v[122:125], v[152:155], v[180:183], v[122:125]
	v_mfma_f32_16x16x32_bf16 v[118:121], v[148:151], v[188:191], v[118:121]
	v_mfma_f32_16x16x32_bf16 v[110:113], v[152:155], v[188:191], v[110:113]
	v_mfma_f32_16x16x32_bf16 v[102:105], v[148:151], v[196:199], v[102:105]
	v_mfma_f32_16x16x32_bf16 v[94:97], v[152:155], v[196:199], v[94:97]
	v_mfma_f32_16x16x32_bf16 v[86:89], v[148:151], v[204:207], v[86:89]
	v_mfma_f32_16x16x32_bf16 v[78:81], v[152:155], v[204:207], v[78:81]
	v_mfma_f32_16x16x32_bf16 v[126:129], v[156:159], v[184:187], v[126:129]
	v_mfma_f32_16x16x32_bf16 v[122:125], v[160:163], v[184:187], v[122:125]
	v_mfma_f32_16x16x32_bf16 v[118:121], v[156:159], v[192:195], v[118:121]
	v_mfma_f32_16x16x32_bf16 v[110:113], v[160:163], v[192:195], v[110:113]
	v_mfma_f32_16x16x32_bf16 v[102:105], v[156:159], v[200:203], v[102:105]
	v_mfma_f32_16x16x32_bf16 v[94:97], v[160:163], v[200:203], v[94:97]
	v_mfma_f32_16x16x32_bf16 v[86:89], v[156:159], v[208:211], v[86:89]
	v_mfma_f32_16x16x32_bf16 v[78:81], v[160:163], v[208:211], v[78:81]
	v_mfma_f32_16x16x32_bf16 v[114:117], v[164:167], v[180:183], v[114:117]
	v_mfma_f32_16x16x32_bf16 v[106:109], v[168:171], v[180:183], v[106:109]
	v_mfma_f32_16x16x32_bf16 v[98:101], v[164:167], v[188:191], v[98:101]
	v_mfma_f32_16x16x32_bf16 v[90:93], v[168:171], v[188:191], v[90:93]
	v_mfma_f32_16x16x32_bf16 v[82:85], v[164:167], v[196:199], v[82:85]
	v_mfma_f32_16x16x32_bf16 v[74:77], v[168:171], v[196:199], v[74:77]
	v_mfma_f32_16x16x32_bf16 v[70:73], v[164:167], v[204:207], v[70:73]
	v_mfma_f32_16x16x32_bf16 v[66:69], v[168:171], v[204:207], v[66:69]
	v_mfma_f32_16x16x32_bf16 v[114:117], v[172:175], v[184:187], v[114:117]
	v_mfma_f32_16x16x32_bf16 v[106:109], v[176:179], v[184:187], v[106:109]
	v_mfma_f32_16x16x32_bf16 v[98:101], v[172:175], v[192:195], v[98:101]
	v_mfma_f32_16x16x32_bf16 v[90:93], v[176:179], v[192:195], v[90:93]
	v_mfma_f32_16x16x32_bf16 v[82:85], v[172:175], v[200:203], v[82:85]
	v_mfma_f32_16x16x32_bf16 v[74:77], v[176:179], v[200:203], v[74:77]
	v_mfma_f32_16x16x32_bf16 v[70:73], v[172:175], v[208:211], v[70:73]
	v_mfma_f32_16x16x32_bf16 v[66:69], v[176:179], v[208:211], v[66:69]
	s_barrier
	s_add_i32 s2, s12, s15
	v_lshl_add_u64 v[214:215], s[94:95], 0, v[132:133]
	s_mov_b32 m0, s2
	ds_read_b128 v[180:183], v145 offset:49152
	ds_read_b128 v[184:187], v145 offset:50176
	ds_read_b128 v[188:191], v145 offset:51200
	ds_read_b128 v[192:195], v145 offset:52224
	ds_read_b128 v[196:199], v145 offset:53248
	ds_read_b128 v[200:203], v145 offset:54272
	ds_read_b128 v[204:207], v145 offset:55296
	ds_read_b128 v[208:211], v145 offset:56320
	global_load_lds_dwordx4 v[214:215], off
	s_add_i32 m0, s2, 0x2000
	s_add_u32 s2, s92, 0x189000
	v_lshl_add_u64 v[214:215], s[94:95], 0, v[136:137]
	s_addc_u32 s3, s93, 0
	s_add_i32 s4, s13, s15
	global_load_lds_dwordx4 v[214:215], off
	v_lshl_add_u64 v[214:215], s[2:3], 0, v[132:133]
	s_mov_b32 m0, s4
	v_lshl_add_u64 v[140:141], v[140:141], 0, s[52:53]
	global_load_lds_dwordx4 v[214:215], off
	v_lshl_add_u64 v[214:215], s[2:3], 0, v[136:137]
	s_add_i32 m0, s4, 0x2000
	s_nop 0
	global_load_lds_dwordx4 v[214:215], off
	s_mov_b32 m0, s8
	s_nop 0
	global_load_lds_dwordx4 v[140:141], off
	v_lshl_add_u64 v[140:141], v[212:213], 0, s[52:53]
	s_mov_b32 m0, s9
	s_nop 0
	global_load_lds_dwordx4 v[140:141], off
	s_waitcnt vmcnt(8)
	s_waitcnt lgkmcnt(0)
	s_barrier
	s_waitcnt lgkmcnt(0)
	v_mfma_f32_16x16x32_bf16 v[62:65], v[148:151], v[180:183], v[62:65]
	v_mfma_f32_16x16x32_bf16 v[58:61], v[152:155], v[180:183], v[58:61]
	v_mfma_f32_16x16x32_bf16 v[54:57], v[148:151], v[188:191], v[54:57]
	v_mfma_f32_16x16x32_bf16 v[46:49], v[152:155], v[188:191], v[46:49]
	v_mfma_f32_16x16x32_bf16 v[38:41], v[148:151], v[196:199], v[38:41]
	v_mfma_f32_16x16x32_bf16 v[30:33], v[152:155], v[196:199], v[30:33]
	v_mfma_f32_16x16x32_bf16 v[22:25], v[148:151], v[204:207], v[22:25]
	v_mfma_f32_16x16x32_bf16 v[14:17], v[152:155], v[204:207], v[14:17]
	v_mfma_f32_16x16x32_bf16 v[62:65], v[156:159], v[184:187], v[62:65]
	v_mfma_f32_16x16x32_bf16 v[58:61], v[160:163], v[184:187], v[58:61]
	v_mfma_f32_16x16x32_bf16 v[54:57], v[156:159], v[192:195], v[54:57]
	v_mfma_f32_16x16x32_bf16 v[46:49], v[160:163], v[192:195], v[46:49]
	v_mfma_f32_16x16x32_bf16 v[38:41], v[156:159], v[200:203], v[38:41]
	v_mfma_f32_16x16x32_bf16 v[30:33], v[160:163], v[200:203], v[30:33]
	v_mfma_f32_16x16x32_bf16 v[22:25], v[156:159], v[208:211], v[22:25]
	v_mfma_f32_16x16x32_bf16 v[14:17], v[160:163], v[208:211], v[14:17]
	v_mfma_f32_16x16x32_bf16 v[50:53], v[164:167], v[180:183], v[50:53]
	v_mfma_f32_16x16x32_bf16 v[42:45], v[168:171], v[180:183], v[42:45]
	v_mfma_f32_16x16x32_bf16 v[34:37], v[164:167], v[188:191], v[34:37]
	v_mfma_f32_16x16x32_bf16 v[26:29], v[168:171], v[188:191], v[26:29]
	v_mfma_f32_16x16x32_bf16 v[18:21], v[164:167], v[196:199], v[18:21]
	v_mfma_f32_16x16x32_bf16 v[10:13], v[168:171], v[196:199], v[10:13]
	v_mfma_f32_16x16x32_bf16 v[6:9], v[164:167], v[204:207], v[6:9]
	v_mfma_f32_16x16x32_bf16 v[2:5], v[168:171], v[204:207], v[2:5]
	v_mfma_f32_16x16x32_bf16 v[50:53], v[172:175], v[184:187], v[50:53]
	v_mfma_f32_16x16x32_bf16 v[42:45], v[176:179], v[184:187], v[42:45]
	v_mfma_f32_16x16x32_bf16 v[34:37], v[172:175], v[192:195], v[34:37]
	v_mfma_f32_16x16x32_bf16 v[26:29], v[176:179], v[192:195], v[26:29]
	v_mfma_f32_16x16x32_bf16 v[18:21], v[172:175], v[200:203], v[18:21]
	v_mfma_f32_16x16x32_bf16 v[10:13], v[176:179], v[200:203], v[10:13]
	v_mfma_f32_16x16x32_bf16 v[6:9], v[172:175], v[208:211], v[6:9]
	v_mfma_f32_16x16x32_bf16 v[2:5], v[176:179], v[208:211], v[2:5]
	s_barrier
	s_add_i32 s2, s87, 2
	s_cmp_gt_u32 s87, 61
	s_cbranch_scc1 .LBB0_255
	s_mov_b32 s87, s2
	s_branch .LBB0_220

.LBB0_315:
	s_setprio 0
	s_add_u32 s10, s50, 0x34000000
	s_addc_u32 s11, s51, 0
	s_add_u32 s76, s50, 0x3a400000
	s_addc_u32 s77, s51, 0
	s_cmp_lt_i32 s68, 4
	s_cselect_b64 s[0:1], -1, 0
	s_cmp_gt_i32 s69, 3
	s_cselect_b64 s[2:3], -1, 0
	s_and_b64 s[0:1], s[0:1], s[2:3]
	s_andn2_b64 vcc, exec, s[0:1]
	s_cbranch_vccnz .LBB0_400
	s_waitcnt vmcnt(0)
	v_mov_b32_e32 v22, v0
	v_readlane_b32 s52, v249, 25
	v_and_b32_e32 v19, 63, v22
	v_lshlrev_b32_e32 v18, 3, v19
	v_bfe_u32 v20, v22, 2, 1
	v_and_b32_e32 v1, 24, v18
	v_lshl_or_b32 v21, v20, 6, v1
	v_readlane_b32 s56, v249, 29
	v_readlane_b32 s57, v249, 30
	v_lshlrev_b32_e32 v74, 2, v21
	v_readlane_b32 s58, v249, 31
	v_readlane_b32 s59, v249, 32
	v_readlane_b32 s60, v249, 33
	v_readlane_b32 s61, v249, 34
	v_readlane_b32 s62, v249, 35
	v_readlane_b32 s63, v249, 36
	v_readlane_b32 s64, v249, 37
	v_readlane_b32 s65, v249, 38
	v_readlane_b32 s66, v249, 39
	v_readlane_b32 s67, v249, 40
	s_mov_b64 s[20:21], s[56:57]
	s_mov_b64 s[22:23], s[58:59]
	global_load_dwordx3 v[58:60], v74, s[20:21] offset:16
	global_load_dwordx3 v[62:64], v74, s[22:23] offset:16
	global_load_dwordx4 v[2:5], v74, s[20:21]
	global_load_dwordx4 v[6:9], v74, s[22:23]
	global_load_dwordx3 v[66:68], v74, s[20:21] offset:144
	global_load_dwordx3 v[70:72], v74, s[22:23] offset:144
	global_load_dwordx4 v[10:13], v74, s[20:21] offset:128
	global_load_dwordx4 v[14:17], v74, s[22:23] offset:128
	v_readlane_b32 s22, v249, 51
	s_ashr_i32 s93, s92, 31
	v_readlane_b32 s23, v249, 52
	s_or_b64 s[0:1], s[22:23], s[92:93]
	s_mov_b32 s0, 0
	s_cmp_lg_u64 s[0:1], 0
	v_readfirstlane_b32 s2, v22
	v_readlane_b32 s53, v249, 26
	v_readlane_b32 s54, v249, 27
	v_readlane_b32 s55, v249, 28
	s_mov_b64 s[24:25], s[60:61]
	s_mov_b64 s[26:27], s[62:63]
	s_mov_b64 s[28:29], s[64:65]
	s_mov_b64 s[30:31], s[66:67]
	s_cbranch_scc0 .LBB0_356
	s_ashr_i32 s4, s93, 31
	s_add_u32 s0, s92, s4
	s_mov_b32 s5, s4
	s_addc_u32 s1, s93, s4
	s_xor_b64 s[6:7], s[0:1], s[4:5]
	v_cvt_f32_u32_e32 v22, s6
	v_cvt_f32_u32_e32 v23, s7
	s_sub_u32 s3, 0, s6
	s_subb_u32 s12, 0, s7
	v_fmamk_f32 v22, v23, 0x4f800000, v22
	v_rcp_f32_e32 v22, v22
	s_nop 0
	v_mul_f32_e32 v22, 0x5f7ffffc, v22
	v_mul_f32_e32 v23, 0x2f800000, v22
	v_trunc_f32_e32 v23, v23
	v_fmamk_f32 v22, v23, 0xcf800000, v22
	v_cvt_u32_f32_e32 v23, v23
	v_cvt_u32_f32_e32 v22, v22
	v_readfirstlane_b32 s13, v23
	v_readfirstlane_b32 s8, v22
	s_mul_i32 s9, s3, s13
	s_mul_hi_u32 s15, s3, s8
	s_mul_i32 s14, s12, s8
	s_add_i32 s9, s15, s9
	s_add_i32 s9, s9, s14
	s_mul_i32 s18, s3, s8
	s_mul_i32 s15, s8, s9
	s_mul_hi_u32 s19, s8, s18
	s_mul_hi_u32 s14, s8, s9
	s_add_u32 s15, s19, s15
	s_addc_u32 s14, 0, s14
	s_mul_hi_u32 s20, s13, s18
	s_mul_i32 s18, s13, s18
	s_add_u32 s15, s15, s18
	s_mul_hi_u32 s19, s13, s9
	s_addc_u32 s14, s14, s20
	s_addc_u32 s15, s19, 0
	s_mul_i32 s9, s13, s9
	s_add_u32 s9, s14, s9
	s_addc_u32 s14, 0, s15
	s_add_u32 s15, s8, s9
	s_cselect_b64 s[8:9], -1, 0
	s_cmp_lg_u64 s[8:9], 0
	s_addc_u32 s13, s13, s14
	s_mul_i32 s8, s3, s13
	s_mul_hi_u32 s9, s3, s15
	s_add_i32 s8, s9, s8
	s_mul_i32 s12, s12, s15
	s_add_i32 s8, s8, s12
	s_mul_i32 s3, s3, s15
	s_mul_hi_u32 s12, s13, s3
	s_mul_i32 s14, s13, s3
	s_mul_i32 s19, s15, s8
	s_mul_hi_u32 s3, s15, s3
	s_mul_hi_u32 s18, s15, s8
	s_add_u32 s3, s3, s19
	s_addc_u32 s18, 0, s18
	s_add_u32 s3, s3, s14
	s_mul_hi_u32 s9, s13, s8
	s_addc_u32 s3, s18, s12
	s_addc_u32 s9, s9, 0
	s_mul_i32 s8, s13, s8
	s_add_u32 s3, s3, s8
	s_addc_u32 s12, 0, s9
	s_add_u32 s3, s15, s3
	s_cselect_b64 s[8:9], -1, 0
	s_cmp_lg_u64 s[8:9], 0
	s_addc_u32 s14, s13, s12
	s_ashr_i32 s8, s23, 31
	s_add_u32 s12, s22, s8
	s_mov_b32 s9, s8
	s_addc_u32 s13, s23, s8
	s_xor_b64 s[12:13], s[12:13], s[8:9]
	s_mul_i32 s18, s12, s14
	s_mul_hi_u32 s19, s12, s3
	s_mul_hi_u32 s15, s12, s14
	s_add_u32 s18, s19, s18
	s_addc_u32 s15, 0, s15
	s_mul_hi_u32 s20, s13, s3
	s_mul_i32 s3, s13, s3
	s_add_u32 s3, s18, s3
	s_mul_hi_u32 s19, s13, s14
	s_addc_u32 s3, s15, s20
	s_addc_u32 s15, s19, 0
	s_mul_i32 s14, s13, s14
	s_add_u32 s3, s3, s14
	s_addc_u32 s20, 0, s15
	s_mul_i32 s14, s6, s20
	s_mul_hi_u32 s15, s6, s3
	s_add_i32 s14, s15, s14
	s_mul_i32 s15, s7, s3
	s_add_i32 s21, s14, s15
	s_sub_i32 s18, s13, s21
	s_mul_i32 s14, s6, s3
	s_sub_u32 s12, s12, s14
	s_cselect_b64 s[14:15], -1, 0
	s_cmp_lg_u64 s[14:15], 0
	s_subb_u32 s22, s18, s7
	s_sub_u32 s23, s12, s6
	s_cselect_b64 s[18:19], -1, 0
	s_cmp_lg_u64 s[18:19], 0
	s_subb_u32 s18, s22, 0
	s_cmp_ge_u32 s18, s7
	s_cselect_b32 s19, -1, 0
	s_cmp_ge_u32 s23, s6
	s_cselect_b32 s22, -1, 0
	s_cmp_eq_u32 s18, s7
	s_cselect_b32 s18, s22, s19
	s_add_u32 s19, s3, 1
	s_addc_u32 s22, s20, 0
	s_add_u32 s23, s3, 2
	s_addc_u32 s24, s20, 0
	s_cmp_lg_u32 s18, 0
	s_cselect_b32 s18, s23, s19
	s_cselect_b32 s19, s24, s22
	s_cmp_lg_u64 s[14:15], 0
	s_subb_u32 s13, s13, s21
	s_cmp_ge_u32 s13, s7
	s_cselect_b32 s14, -1, 0
	s_cmp_ge_u32 s12, s6
	s_cselect_b32 s6, -1, 0
	s_cmp_eq_u32 s13, s7
	s_cselect_b32 s6, s6, s14
	s_cmp_lg_u32 s6, 0
	s_cselect_b32 s7, s19, s20
	s_cselect_b32 s6, s18, s3
	s_xor_b64 s[4:5], s[8:9], s[4:5]
	s_xor_b64 s[6:7], s[6:7], s[4:5]
	s_sub_u32 s12, s6, s4
	v_cvt_f32_u32_e32 v22, s92
	s_cbranch_execnz .LBB0_319

.LBB0_519:
	s_add_u32 s19, s50, 0x108000
	s_addc_u32 s52, s51, 0
	s_and_b32 s18, s4, 3
	s_lshl_b32 s20, s3, 13
	s_lshl_b32 s21, s18, 9
	s_add_u32 s4, s78, 0x88800
	s_addc_u32 s5, s79, 0
	s_add_i32 m0, s94, 0x18000
	v_lshl_add_u64 v[8:9], s[4:5], 0, v[140:141]
	s_waitcnt vmcnt(2)
	s_barrier
	global_load_lds_dwordx4 v[8:9], off
	v_lshl_add_u64 v[8:9], s[4:5], 0, v[144:145]
	s_add_i32 m0, s94, 0x1a000
	s_mov_b64 s[56:57], 0x80
	s_add_i32 s53, s94, 0x8000
	s_add_i32 s92, s94, 0xa000
	global_load_lds_dwordx4 v[8:9], off
	v_lshl_add_u64 v[2:3], v[2:3], 0, s[56:57]
	s_mov_b32 m0, s53
	s_add_u32 s4, s78, 0x89000
	global_load_lds_dwordx4 v[2:3], off
	v_lshl_add_u64 v[2:3], v[4:5], 0, s[56:57]
	s_mov_b32 m0, s92
	s_addc_u32 s5, s79, 0
	global_load_lds_dwordx4 v[2:3], off
	s_add_i32 m0, s94, 0x1c000
	v_lshl_add_u64 v[2:3], s[4:5], 0, v[140:141]
	global_load_lds_dwordx4 v[2:3], off
	v_lshl_add_u64 v[2:3], s[4:5], 0, v[144:145]
	s_add_i32 m0, s94, 0x1e000
	v_and_b32_e32 v1, 15, v6
	global_load_lds_dwordx4 v[2:3], off
	v_bfe_u32 v2, v6, 4, 2
	v_lshlrev_b32_e32 v3, 4, v2
	v_lshlrev_b32_e32 v4, 2, v6
	v_lshl_or_b32 v3, v1, 6, v3
	v_and_b32_e32 v4, 32, v4
	v_lshlrev_b32_e32 v2, 11, v2
	v_lshlrev_b32_e32 v1, 4, v1
	v_bitop3_b32 v18, v3, s20, v4 bitop3:0xde
	v_or3_b32 v1, s21, v1, v2
	v_and_b32_e32 v2, 3, v6
	v_and_b32_e32 v3, 60, v6
	s_cmpk_lt_u32 s14, 0x100
	v_lshl_or_b32 v184, v2, 6, v3
	v_bfe_u32 v3, v6, 2, 4
	v_lshlrev_b32_e32 v2, 3, v2
	v_readlane_b32 s4, v249, 49
	s_cselect_b64 s[58:59], -1, 0
	v_lshl_or_b32 v185, s18, 5, v2
	v_lshl_or_b32 v2, s3, 6, v3
	s_ashr_i32 s3, s4, 31
	v_readlane_b32 s5, v249, 50
	v_writelane_b32 v249, s3, 60
	s_waitcnt vmcnt(6)
	v_or_b32_e32 v4, 16, v2
	v_readlane_b32 s4, v249, 2
	s_ashr_i32 s3, s4, 31
	v_readlane_b32 s5, v249, 3
	v_writelane_b32 v249, s3, 61
	s_and_b32 s3, s4, 4
	v_writelane_b32 v249, s3, 62
	s_bfe_u32 s3, s4, 0x30003
	v_writelane_b32 v249, s3, 63
	s_lshl_b32 s3, s4, 2
	s_and_b32 s3, s3, 12
	s_ashr_i32 s4, s4, 6
	v_or_b32_e32 v6, 32, v2
	v_or_b32_e32 v8, 48, v2
	v_add_u32_e32 v10, 0x80, v2
	v_add_u32_e32 v12, 0x90, v2
	v_add_u32_e32 v14, 0xa0, v2
	v_add_u32_e32 v16, 0xb0, v2
	s_add_i32 s3, s3, s4
	v_ashrrev_i32_e32 v3, 31, v2
	v_ashrrev_i32_e32 v5, 31, v4
	v_ashrrev_i32_e32 v7, 31, v6
	v_ashrrev_i32_e32 v9, 31, v8
	v_ashrrev_i32_e32 v11, 31, v10
	v_ashrrev_i32_e32 v13, 31, v12
	v_ashrrev_i32_e32 v15, 31, v14
	v_ashrrev_i32_e32 v17, 31, v16
	v_writelane_b32 v248, s3, 3
	s_movk_i32 s3, 0x2080
	v_lshlrev_b64 v[146:147], 14, v[2:3]
	v_lshlrev_b64 v[148:149], 14, v[4:5]
	v_lshlrev_b64 v[150:151], 14, v[6:7]
	v_lshlrev_b64 v[152:153], 14, v[8:9]
	v_lshlrev_b64 v[154:155], 14, v[10:11]
	v_lshlrev_b64 v[156:157], 14, v[12:13]
	v_lshlrev_b64 v[158:159], 14, v[14:15]
	v_lshlrev_b64 v[160:161], 14, v[16:17]
	v_mad_i64_i32 v[162:163], s[4:5], v2, s3, 0
	v_mad_i64_i32 v[164:165], s[4:5], v4, s3, 0
	v_mad_i64_i32 v[166:167], s[4:5], v6, s3, 0
	v_mad_i64_i32 v[168:169], s[4:5], v8, s3, 0
	v_mad_i64_i32 v[170:171], s[4:5], v10, s3, 0
	v_mad_i64_i32 v[172:173], s[4:5], v12, s3, 0
	v_mad_i64_i32 v[174:175], s[4:5], v14, s3, 0
	v_mad_i64_i32 v[176:177], s[4:5], v16, s3, 0
	v_mov_b32_e32 v187, s2
	s_add_i32 s93, 0, 0x10000
	s_add_i32 s18, 0, 0x14000
	v_add_u32_e32 v186, 0, v18
	v_mov_b64_e32 v[178:179], 0x2ff
	s_mov_b32 s36, 0
	s_barrier
	v_readfirstlane_b32 s98, v0
	s_nop 3
	s_and_b32 s98, s98, 0x3ff
	s_cmp_ge_u32 s98, 0x100
	s_cbranch_scc0 .Lprio_done1
	s_setprio 1
.Lprio_done1:
	s_branch .LBB0_522
.LBB0_520:
	s_mov_b64 s[2:3], 0

.LBB0_558:
	s_lshl_b32 s2, s69, 7
	s_add_u32 s20, s74, s2
	s_addc_u32 s21, s75, 0
	s_add_u32 s4, s20, 0x100
	s_addc_u32 s5, s21, 0
	s_and_b64 s[2:3], s[82:83], exec
	s_mul_i32 s2, s69, 0x88800
	v_add_u32_e32 v188, s93, v1
	v_add_u32_e32 v204, s18, v1
	s_cselect_b32 s5, s5, s63
	s_cselect_b32 s4, s4, s62
	s_add_u32 s2, s78, s2
	ds_read_b128 v[130:133], v188
	ds_read_b128 v[134:137], v188 offset:256
	ds_read_b128 v[180:183], v188 offset:8192
	ds_read_b128 v[188:191], v188 offset:8448
	ds_read_b128 v[192:195], v204
	ds_read_b128 v[196:199], v204 offset:256
	ds_read_b128 v[200:203], v204 offset:8192
	ds_read_b128 v[204:207], v204 offset:8448
	s_addc_u32 s3, s79, 0
	s_add_u32 s22, s2, 0x111000
	s_addc_u32 s23, s3, 0
	s_and_b64 s[2:3], s[82:83], exec
	s_cselect_b32 s82, s22, s61
	s_cselect_b32 s83, s23, s14
	s_add_u32 s84, s82, 0x88800
	s_addc_u32 s85, s83, 0
	s_add_u32 s2, s20, 0x104080
	s_addc_u32 s3, s21, 0
	v_lshl_add_u64 v[240:241], s[2:3], 0, v[138:139]
	s_add_i32 m0, s94, 0xc000
	ds_read_b128 v[208:211], v186
	ds_read_b128 v[212:215], v186 offset:1024
	ds_read_b128 v[216:219], v186 offset:2048
	ds_read_b128 v[220:223], v186 offset:3072
	ds_read_b128 v[224:227], v186 offset:4096
	ds_read_b128 v[228:231], v186 offset:5120
	ds_read_b128 v[232:235], v186 offset:6144
	ds_read_b128 v[236:239], v186 offset:7168
	global_load_lds_dwordx4 v[240:241], off
	v_lshl_add_u64 v[240:241], s[2:3], 0, v[142:143]
	s_add_i32 m0, s94, 0xe000
	s_nop 0
	global_load_lds_dwordx4 v[240:241], off
	s_waitcnt vmcnt(8)
	s_waitcnt lgkmcnt(0)
	s_barrier
	s_waitcnt lgkmcnt(0)
	v_mfma_f32_16x16x32_bf16 v[126:129], v[130:133], v[208:211], v[126:129]
	v_mfma_f32_16x16x32_bf16 v[122:125], v[134:137], v[208:211], v[122:125]
	v_mfma_f32_16x16x32_bf16 v[110:113], v[130:133], v[216:219], v[110:113]
	v_mfma_f32_16x16x32_bf16 v[106:109], v[134:137], v[216:219], v[106:109]
	v_mfma_f32_16x16x32_bf16 v[94:97], v[130:133], v[224:227], v[94:97]
	v_mfma_f32_16x16x32_bf16 v[90:93], v[134:137], v[224:227], v[90:93]
	v_mfma_f32_16x16x32_bf16 v[78:81], v[130:133], v[232:235], v[78:81]
	v_mfma_f32_16x16x32_bf16 v[74:77], v[134:137], v[232:235], v[74:77]
	v_mfma_f32_16x16x32_bf16 v[126:129], v[180:183], v[212:215], v[126:129]
	v_mfma_f32_16x16x32_bf16 v[122:125], v[188:191], v[212:215], v[122:125]
	v_mfma_f32_16x16x32_bf16 v[110:113], v[180:183], v[220:223], v[110:113]
	v_mfma_f32_16x16x32_bf16 v[106:109], v[188:191], v[220:223], v[106:109]
	v_mfma_f32_16x16x32_bf16 v[94:97], v[180:183], v[228:231], v[94:97]
	v_mfma_f32_16x16x32_bf16 v[90:93], v[188:191], v[228:231], v[90:93]
	v_mfma_f32_16x16x32_bf16 v[78:81], v[180:183], v[236:239], v[78:81]
	v_mfma_f32_16x16x32_bf16 v[74:77], v[188:191], v[236:239], v[74:77]
	v_mfma_f32_16x16x32_bf16 v[118:121], v[192:195], v[208:211], v[118:121]
	v_mfma_f32_16x16x32_bf16 v[114:117], v[196:199], v[208:211], v[114:117]
	v_mfma_f32_16x16x32_bf16 v[102:105], v[192:195], v[216:219], v[102:105]
	v_mfma_f32_16x16x32_bf16 v[98:101], v[196:199], v[216:219], v[98:101]
	v_mfma_f32_16x16x32_bf16 v[86:89], v[192:195], v[224:227], v[86:89]
	v_mfma_f32_16x16x32_bf16 v[82:85], v[196:199], v[224:227], v[82:85]
	v_mfma_f32_16x16x32_bf16 v[70:73], v[192:195], v[232:235], v[70:73]
	v_mfma_f32_16x16x32_bf16 v[66:69], v[196:199], v[232:235], v[66:69]
	v_mfma_f32_16x16x32_bf16 v[118:121], v[200:203], v[212:215], v[118:121]
	v_mfma_f32_16x16x32_bf16 v[114:117], v[204:207], v[212:215], v[114:117]
	v_mfma_f32_16x16x32_bf16 v[102:105], v[200:203], v[220:223], v[102:105]
	v_mfma_f32_16x16x32_bf16 v[98:101], v[204:207], v[220:223], v[98:101]
	v_mfma_f32_16x16x32_bf16 v[86:89], v[200:203], v[228:231], v[86:89]
	v_mfma_f32_16x16x32_bf16 v[82:85], v[204:207], v[228:231], v[82:85]
	v_mfma_f32_16x16x32_bf16 v[70:73], v[200:203], v[236:239], v[70:73]
	v_mfma_f32_16x16x32_bf16 v[66:69], v[204:207], v[236:239], v[66:69]
	s_barrier
	s_add_i32 s2, s93, s73
	v_lshl_add_u64 v[240:241], s[82:83], 0, v[140:141]
	s_mov_b32 m0, s2
	ds_read_b128 v[208:211], v186 offset:16384
	ds_read_b128 v[212:215], v186 offset:17408
	ds_read_b128 v[216:219], v186 offset:18432
	ds_read_b128 v[220:223], v186 offset:19456
	ds_read_b128 v[224:227], v186 offset:20480
	ds_read_b128 v[228:231], v186 offset:21504
	ds_read_b128 v[232:235], v186 offset:22528
	ds_read_b128 v[236:239], v186 offset:23552
	global_load_lds_dwordx4 v[240:241], off
	v_lshl_add_u64 v[242:243], s[82:83], 0, v[144:145]
	s_add_i32 m0, s2, 0x2000
	s_add_i32 s2, s18, s73
	global_load_lds_dwordx4 v[242:243], off
	v_lshl_add_u64 v[240:241], v[240:241], 0, s[12:13]
	s_mov_b32 m0, s2
	s_nop 0
	global_load_lds_dwordx4 v[240:241], off
	v_lshl_add_u64 v[240:241], v[242:243], 0, s[12:13]
	s_add_i32 m0, s2, 0x2000
	v_lshl_add_u64 v[242:243], s[4:5], 0, v[142:143]
	global_load_lds_dwordx4 v[240:241], off
	v_lshl_add_u64 v[240:241], s[4:5], 0, v[138:139]
	s_mov_b32 m0, s94
	s_nop 0
	global_load_lds_dwordx4 v[240:241], off
	s_mov_b32 m0, s95
	s_nop 0
	global_load_lds_dwordx4 v[242:243], off
	s_waitcnt vmcnt(8)
	s_waitcnt lgkmcnt(0)
	s_barrier
	s_waitcnt lgkmcnt(0)
	v_mfma_f32_16x16x32_bf16 v[62:65], v[130:133], v[208:211], v[62:65]
	v_mfma_f32_16x16x32_bf16 v[58:61], v[134:137], v[208:211], v[58:61]
	v_mfma_f32_16x16x32_bf16 v[46:49], v[130:133], v[216:219], v[46:49]
	v_mfma_f32_16x16x32_bf16 v[42:45], v[134:137], v[216:219], v[42:45]
	v_mfma_f32_16x16x32_bf16 v[30:33], v[130:133], v[224:227], v[30:33]
	v_mfma_f32_16x16x32_bf16 v[26:29], v[134:137], v[224:227], v[26:29]
	v_mfma_f32_16x16x32_bf16 v[14:17], v[130:133], v[232:235], v[14:17]
	v_mfma_f32_16x16x32_bf16 v[10:13], v[134:137], v[232:235], v[10:13]
	v_mfma_f32_16x16x32_bf16 v[62:65], v[180:183], v[212:215], v[62:65]
	v_mfma_f32_16x16x32_bf16 v[58:61], v[188:191], v[212:215], v[58:61]
	v_mfma_f32_16x16x32_bf16 v[46:49], v[180:183], v[220:223], v[46:49]
	v_mfma_f32_16x16x32_bf16 v[42:45], v[188:191], v[220:223], v[42:45]
	v_mfma_f32_16x16x32_bf16 v[30:33], v[180:183], v[228:231], v[30:33]
	v_mfma_f32_16x16x32_bf16 v[26:29], v[188:191], v[228:231], v[26:29]
	v_mfma_f32_16x16x32_bf16 v[14:17], v[180:183], v[236:239], v[14:17]
	v_mfma_f32_16x16x32_bf16 v[10:13], v[188:191], v[236:239], v[10:13]
	v_mfma_f32_16x16x32_bf16 v[54:57], v[192:195], v[208:211], v[54:57]
	v_mfma_f32_16x16x32_bf16 v[50:53], v[196:199], v[208:211], v[50:53]
	v_mfma_f32_16x16x32_bf16 v[38:41], v[192:195], v[216:219], v[38:41]
	v_mfma_f32_16x16x32_bf16 v[34:37], v[196:199], v[216:219], v[34:37]
	v_mfma_f32_16x16x32_bf16 v[22:25], v[192:195], v[224:227], v[22:25]
	v_mfma_f32_16x16x32_bf16 v[18:21], v[196:199], v[224:227], v[18:21]
	v_mfma_f32_16x16x32_bf16 v[6:9], v[192:195], v[232:235], v[6:9]
	v_mfma_f32_16x16x32_bf16 v[2:5], v[196:199], v[232:235], v[2:5]
	v_mfma_f32_16x16x32_bf16 v[54:57], v[200:203], v[212:215], v[54:57]
	v_mfma_f32_16x16x32_bf16 v[50:53], v[204:207], v[212:215], v[50:53]
	v_mfma_f32_16x16x32_bf16 v[38:41], v[200:203], v[220:223], v[38:41]
	v_mfma_f32_16x16x32_bf16 v[34:37], v[204:207], v[220:223], v[34:37]
	v_mfma_f32_16x16x32_bf16 v[22:25], v[200:203], v[228:231], v[22:25]
	v_mfma_f32_16x16x32_bf16 v[18:21], v[204:207], v[228:231], v[18:21]
	v_mfma_f32_16x16x32_bf16 v[6:9], v[200:203], v[236:239], v[6:9]
	v_mfma_f32_16x16x32_bf16 v[2:5], v[204:207], v[236:239], v[2:5]
	s_barrier
	s_add_i32 s20, 0, 0x18000
	s_add_i32 s21, 0, 0x1c000
	v_add_u32_e32 v188, s20, v1
	v_add_u32_e32 v204, s21, v1
	ds_read_b128 v[130:133], v188
	ds_read_b128 v[134:137], v188 offset:256
	ds_read_b128 v[180:183], v188 offset:8192
	ds_read_b128 v[188:191], v188 offset:8448
	ds_read_b128 v[192:195], v204
	ds_read_b128 v[196:199], v204 offset:256
	ds_read_b128 v[200:203], v204 offset:8192
	ds_read_b128 v[204:207], v204 offset:8448
	s_add_u32 s2, s4, 0x104000
	s_addc_u32 s3, s5, 0
	s_mov_b32 m0, s96
	v_lshl_add_u64 v[244:245], s[2:3], 0, v[138:139]
	ds_read_b128 v[208:211], v186 offset:32768
	ds_read_b128 v[212:215], v186 offset:33792
	ds_read_b128 v[216:219], v186 offset:34816
	ds_read_b128 v[220:223], v186 offset:35840
	ds_read_b128 v[224:227], v186 offset:36864
	ds_read_b128 v[228:231], v186 offset:37888
	ds_read_b128 v[232:235], v186 offset:38912
	ds_read_b128 v[236:239], v186 offset:39936
	global_load_lds_dwordx4 v[244:245], off
	v_lshl_add_u64 v[244:245], s[2:3], 0, v[142:143]
	s_mov_b32 m0, s97
	s_nop 0
	global_load_lds_dwordx4 v[244:245], off
	s_waitcnt vmcnt(8)
	s_waitcnt lgkmcnt(0)
	s_barrier
	s_waitcnt lgkmcnt(0)
	v_mfma_f32_16x16x32_bf16 v[126:129], v[130:133], v[208:211], v[126:129]
	v_mfma_f32_16x16x32_bf16 v[122:125], v[134:137], v[208:211], v[122:125]
	v_mfma_f32_16x16x32_bf16 v[110:113], v[130:133], v[216:219], v[110:113]
	v_mfma_f32_16x16x32_bf16 v[106:109], v[134:137], v[216:219], v[106:109]
	v_mfma_f32_16x16x32_bf16 v[94:97], v[130:133], v[224:227], v[94:97]
	v_mfma_f32_16x16x32_bf16 v[90:93], v[134:137], v[224:227], v[90:93]
	v_mfma_f32_16x16x32_bf16 v[78:81], v[130:133], v[232:235], v[78:81]
	v_mfma_f32_16x16x32_bf16 v[74:77], v[134:137], v[232:235], v[74:77]
	v_mfma_f32_16x16x32_bf16 v[126:129], v[180:183], v[212:215], v[126:129]
	v_mfma_f32_16x16x32_bf16 v[122:125], v[188:191], v[212:215], v[122:125]
	v_mfma_f32_16x16x32_bf16 v[110:113], v[180:183], v[220:223], v[110:113]
	v_mfma_f32_16x16x32_bf16 v[106:109], v[188:191], v[220:223], v[106:109]
	v_mfma_f32_16x16x32_bf16 v[94:97], v[180:183], v[228:231], v[94:97]
	v_mfma_f32_16x16x32_bf16 v[90:93], v[188:191], v[228:231], v[90:93]
	v_mfma_f32_16x16x32_bf16 v[78:81], v[180:183], v[236:239], v[78:81]
	v_mfma_f32_16x16x32_bf16 v[74:77], v[188:191], v[236:239], v[74:77]
	v_mfma_f32_16x16x32_bf16 v[118:121], v[192:195], v[208:211], v[118:121]
	v_mfma_f32_16x16x32_bf16 v[114:117], v[196:199], v[208:211], v[114:117]
	v_mfma_f32_16x16x32_bf16 v[102:105], v[192:195], v[216:219], v[102:105]
	v_mfma_f32_16x16x32_bf16 v[98:101], v[196:199], v[216:219], v[98:101]
	v_mfma_f32_16x16x32_bf16 v[86:89], v[192:195], v[224:227], v[86:89]
	v_mfma_f32_16x16x32_bf16 v[82:85], v[196:199], v[224:227], v[82:85]
	v_mfma_f32_16x16x32_bf16 v[70:73], v[192:195], v[232:235], v[70:73]
	v_mfma_f32_16x16x32_bf16 v[66:69], v[196:199], v[232:235], v[66:69]
	v_mfma_f32_16x16x32_bf16 v[118:121], v[200:203], v[212:215], v[118:121]
	v_mfma_f32_16x16x32_bf16 v[114:117], v[204:207], v[212:215], v[114:117]
	v_mfma_f32_16x16x32_bf16 v[102:105], v[200:203], v[220:223], v[102:105]
	v_mfma_f32_16x16x32_bf16 v[98:101], v[204:207], v[220:223], v[98:101]
	v_mfma_f32_16x16x32_bf16 v[86:89], v[200:203], v[228:231], v[86:89]
	v_mfma_f32_16x16x32_bf16 v[82:85], v[204:207], v[228:231], v[82:85]
	v_mfma_f32_16x16x32_bf16 v[70:73], v[200:203], v[236:239], v[70:73]
	v_mfma_f32_16x16x32_bf16 v[66:69], v[204:207], v[236:239], v[66:69]
	s_barrier
	s_add_i32 s2, s20, s73
	v_lshl_add_u64 v[244:245], s[84:85], 0, v[140:141]
	s_mov_b32 m0, s2
	ds_read_b128 v[208:211], v186 offset:49152
	ds_read_b128 v[212:215], v186 offset:50176
	ds_read_b128 v[216:219], v186 offset:51200
	ds_read_b128 v[220:223], v186 offset:52224
	ds_read_b128 v[224:227], v186 offset:53248
	ds_read_b128 v[228:231], v186 offset:54272
	ds_read_b128 v[232:235], v186 offset:55296
	ds_read_b128 v[236:239], v186 offset:56320
	global_load_lds_dwordx4 v[244:245], off
	s_add_i32 m0, s2, 0x2000
	s_add_u32 s2, s82, 0x89000
	v_lshl_add_u64 v[244:245], s[84:85], 0, v[144:145]
	s_addc_u32 s3, s83, 0
	s_add_i32 s4, s21, s73
	global_load_lds_dwordx4 v[244:245], off
	v_lshl_add_u64 v[244:245], s[2:3], 0, v[140:141]
	s_mov_b32 m0, s4
	v_lshl_add_u64 v[240:241], v[240:241], 0, s[56:57]
	global_load_lds_dwordx4 v[244:245], off
	v_lshl_add_u64 v[244:245], s[2:3], 0, v[144:145]
	s_add_i32 m0, s4, 0x2000
	s_nop 0
	global_load_lds_dwordx4 v[244:245], off
	s_mov_b32 m0, s53
	s_nop 0
	global_load_lds_dwordx4 v[240:241], off
	v_lshl_add_u64 v[240:241], v[242:243], 0, s[56:57]
	s_mov_b32 m0, s92
	s_nop 0
	global_load_lds_dwordx4 v[240:241], off
	s_waitcnt vmcnt(8)
	s_waitcnt lgkmcnt(0)
	s_barrier
	s_waitcnt lgkmcnt(0)
	v_mfma_f32_16x16x32_bf16 v[62:65], v[130:133], v[208:211], v[62:65]
	v_mfma_f32_16x16x32_bf16 v[58:61], v[134:137], v[208:211], v[58:61]
	v_mfma_f32_16x16x32_bf16 v[46:49], v[130:133], v[216:219], v[46:49]
	v_mfma_f32_16x16x32_bf16 v[42:45], v[134:137], v[216:219], v[42:45]
	v_mfma_f32_16x16x32_bf16 v[30:33], v[130:133], v[224:227], v[30:33]
	v_mfma_f32_16x16x32_bf16 v[26:29], v[134:137], v[224:227], v[26:29]
	v_mfma_f32_16x16x32_bf16 v[14:17], v[130:133], v[232:235], v[14:17]
	v_mfma_f32_16x16x32_bf16 v[10:13], v[134:137], v[232:235], v[10:13]
	v_mfma_f32_16x16x32_bf16 v[62:65], v[180:183], v[212:215], v[62:65]
	v_mfma_f32_16x16x32_bf16 v[58:61], v[188:191], v[212:215], v[58:61]
	v_mfma_f32_16x16x32_bf16 v[46:49], v[180:183], v[220:223], v[46:49]
	v_mfma_f32_16x16x32_bf16 v[42:45], v[188:191], v[220:223], v[42:45]
	v_mfma_f32_16x16x32_bf16 v[30:33], v[180:183], v[228:231], v[30:33]
	v_mfma_f32_16x16x32_bf16 v[26:29], v[188:191], v[228:231], v[26:29]
	v_mfma_f32_16x16x32_bf16 v[14:17], v[180:183], v[236:239], v[14:17]
	v_mfma_f32_16x16x32_bf16 v[10:13], v[188:191], v[236:239], v[10:13]
	v_mfma_f32_16x16x32_bf16 v[54:57], v[192:195], v[208:211], v[54:57]
	v_mfma_f32_16x16x32_bf16 v[50:53], v[196:199], v[208:211], v[50:53]
	v_mfma_f32_16x16x32_bf16 v[38:41], v[192:195], v[216:219], v[38:41]
	v_mfma_f32_16x16x32_bf16 v[34:37], v[196:199], v[216:219], v[34:37]
	v_mfma_f32_16x16x32_bf16 v[22:25], v[192:195], v[224:227], v[22:25]
	v_mfma_f32_16x16x32_bf16 v[18:21], v[196:199], v[224:227], v[18:21]
	v_mfma_f32_16x16x32_bf16 v[6:9], v[192:195], v[232:235], v[6:9]
	v_mfma_f32_16x16x32_bf16 v[2:5], v[196:199], v[232:235], v[2:5]
	v_mfma_f32_16x16x32_bf16 v[54:57], v[200:203], v[212:215], v[54:57]
	v_mfma_f32_16x16x32_bf16 v[50:53], v[204:207], v[212:215], v[50:53]
	v_mfma_f32_16x16x32_bf16 v[38:41], v[200:203], v[220:223], v[38:41]
	v_mfma_f32_16x16x32_bf16 v[34:37], v[204:207], v[220:223], v[34:37]
	v_mfma_f32_16x16x32_bf16 v[22:25], v[200:203], v[228:231], v[22:25]
	v_mfma_f32_16x16x32_bf16 v[18:21], v[204:207], v[228:231], v[18:21]
	v_mfma_f32_16x16x32_bf16 v[6:9], v[200:203], v[236:239], v[6:9]
	v_mfma_f32_16x16x32_bf16 v[2:5], v[204:207], v[236:239], v[2:5]
	s_barrier
	s_add_i32 s2, s69, 2
	s_cmp_gt_u32 s69, 61
	s_cbranch_scc1 .LBB0_564
	s_mov_b32 s69, s2
	s_branch .LBB0_529

.LBB0_628:
	s_setprio 0
	s_add_u32 s52, s50, 0x8a00000
	s_addc_u32 s53, s51, 0
	s_cmp_lt_i32 s68, 7
	s_cselect_b64 s[2:3], -1, 0
	s_cmp_gt_i32 s69, 6
	s_cselect_b64 s[4:5], -1, 0
	s_and_b64 s[2:3], s[2:3], s[4:5]
	s_andn2_b64 vcc, exec, s[2:3]
	s_cbranch_vccnz .LBB0_726
	v_mov_b32_e32 v1, v0
	s_lshl_b32 s4, s70, 3
	v_readfirstlane_b32 s2, v1
	s_ashr_i32 s2, s2, 6
	s_add_i32 s4, s4, s2
	s_add_i32 s2, s4, 0x8000
	s_cmp_gt_i32 s2, 0xffff
	s_cbranch_scc1 .LBB0_644
	s_waitcnt vmcnt(0)
	v_lshlrev_b32_e32 v3, 2, v1
	s_waitcnt lgkmcnt(1)
	v_lshlrev_b32_e32 v4, 4, v1
	v_lshlrev_b32_e32 v1, 1, v1
	v_and_b32_e32 v2, 0xfc, v3
	v_mov_b32_e32 v35, 0
	v_and_b32_e32 v3, 0xe0, v3
	v_and_b32_e32 v4, 16, v4
	v_and_b32_e32 v1, 12, v1
	s_lshl_b32 s3, s92, 3
	s_lshl_b32 s18, s92, 4
	v_or3_b32 v34, v4, v3, v1
	s_not_b32 s19, s4
	s_mov_b32 s7, 0
	v_lshlrev_b32_e32 v36, 2, v2
	v_mov_b32_e32 v37, v35
	s_branch .LBB0_632

.LBB0_757:
	s_and_b32 s22, s4, 3
	s_lshl_b32 s23, s3, 13
	s_lshl_b32 s24, s22, 9
	s_add_u32 s4, s56, 0x208800
	s_addc_u32 s5, s57, 0
	s_add_i32 m0, s36, 0x18000
	v_lshl_add_u64 v[8:9], s[4:5], 0, v[132:133]
	s_waitcnt vmcnt(2)
	s_barrier
	global_load_lds_dwordx4 v[8:9], off
	v_lshl_add_u64 v[8:9], s[4:5], 0, v[136:137]
	s_add_i32 m0, s36, 0x1a000
	s_mov_b64 s[14:15], 0x80
	s_add_i32 s77, s36, 0x8000
	s_add_i32 s78, s36, 0xa000
	global_load_lds_dwordx4 v[8:9], off
	v_lshl_add_u64 v[2:3], v[2:3], 0, s[14:15]
	s_mov_b32 m0, s77
	s_add_u32 s4, s56, 0x209000
	global_load_lds_dwordx4 v[2:3], off
	v_lshl_add_u64 v[2:3], v[4:5], 0, s[14:15]
	s_mov_b32 m0, s78
	s_addc_u32 s5, s57, 0
	global_load_lds_dwordx4 v[2:3], off
	s_add_i32 m0, s36, 0x1c000
	v_lshl_add_u64 v[2:3], s[4:5], 0, v[132:133]
	global_load_lds_dwordx4 v[2:3], off
	v_lshl_add_u64 v[2:3], s[4:5], 0, v[136:137]
	s_add_i32 m0, s36, 0x1e000
	v_and_b32_e32 v1, 15, v6
	global_load_lds_dwordx4 v[2:3], off
	v_bfe_u32 v2, v6, 4, 2
	v_lshlrev_b32_e32 v3, 4, v2
	v_lshl_or_b32 v3, v1, 6, v3
	v_lshlrev_b32_e32 v4, 2, v6
	v_lshlrev_b32_e32 v2, 11, v2
	v_lshlrev_b32_e32 v1, 4, v1
	v_and_b32_e32 v4, 32, v4
	v_or3_b32 v1, s24, v1, v2
	s_cmpk_lt_u32 s20, 0x100
	v_bfe_u32 v2, v6, 2, 4
	v_readlane_b32 s4, v249, 2
	v_bitop3_b32 v3, v3, s23, v4 bitop3:0xde
	s_waitcnt vmcnt(6)
	s_cselect_b64 s[30:31], -1, 0
	v_and_b32_e32 v4, 3, v6
	v_lshl_or_b32 v143, s3, 6, v2
	s_lshl_b32 s3, s4, 2
	v_and_b32_e32 v5, 60, v6
	v_lshlrev_b32_e32 v2, 3, v4
	s_and_b32 s82, s3, 28
	s_ashr_i32 s3, s4, 6
	v_lshl_or_b32 v142, v4, 6, v5
	v_lshl_or_b32 v144, s22, 5, v2
	s_ashr_i32 s79, s92, 31
	s_ashr_i32 s80, s4, 31
	s_bfe_u32 s81, s4, 0x30003
	s_add_i32 s82, s82, s3
	v_mov_b32_e32 v146, s2
	s_add_i32 s83, 0, 0x10000
	s_add_i32 s84, 0, 0x14000
	v_add_u32_e32 v145, 0, v3
	s_mov_b32 s85, 0x8080
	v_mov_b64_e32 v[138:139], 0xbff
	s_barrier
	v_readlane_b32 s5, v249, 3
	v_readfirstlane_b32 s98, v0
	s_nop 3
	s_and_b32 s98, s98, 0x3ff
	s_cmp_ge_u32 s98, 0x100
	s_cbranch_scc0 .Lprio_done2
	s_setprio 1
.Lprio_done2:
	s_branch .LBB0_760
.LBB0_758:
	s_mov_b64 s[2:3], 0

.LBB0_796:
	s_lshl_b32 s2, s90, 7
	s_add_u32 s20, s54, s2
	s_addc_u32 s21, s55, 0
	s_add_u32 s4, s20, 0x100
	s_addc_u32 s5, s21, 0
	s_and_b64 s[2:3], s[60:61], exec
	v_add_u32_e32 v140, s83, v1
	s_mul_i32 s2, s90, 0x208800
	ds_read_b128 v[148:151], v140
	ds_read_b128 v[152:155], v140 offset:256
	ds_read_b128 v[156:159], v140 offset:8192
	ds_read_b128 v[160:163], v140 offset:8448
	v_add_u32_e32 v140, s84, v1
	s_cselect_b32 s5, s5, s43
	s_cselect_b32 s4, s4, s42
	s_add_u32 s2, s56, s2
	ds_read_b128 v[164:167], v140
	ds_read_b128 v[168:171], v140 offset:256
	ds_read_b128 v[172:175], v140 offset:8192
	ds_read_b128 v[176:179], v140 offset:8448
	s_addc_u32 s3, s57, 0
	s_add_u32 s22, s2, 0x411000
	s_addc_u32 s23, s3, 0
	s_and_b64 s[2:3], s[60:61], exec
	s_cselect_b32 s60, s22, s89
	s_cselect_b32 s61, s23, s35
	s_add_u32 s62, s60, 0x208800
	s_addc_u32 s63, s61, 0
	s_add_u32 s2, s20, 0x104080
	s_addc_u32 s3, s21, 0
	v_lshl_add_u64 v[140:141], s[2:3], 0, v[130:131]
	s_add_i32 m0, s36, 0xc000
	ds_read_b128 v[180:183], v145
	ds_read_b128 v[184:187], v145 offset:1024
	ds_read_b128 v[188:191], v145 offset:2048
	ds_read_b128 v[192:195], v145 offset:3072
	ds_read_b128 v[196:199], v145 offset:4096
	ds_read_b128 v[200:203], v145 offset:5120
	ds_read_b128 v[204:207], v145 offset:6144
	ds_read_b128 v[208:211], v145 offset:7168
	global_load_lds_dwordx4 v[140:141], off
	v_lshl_add_u64 v[140:141], s[2:3], 0, v[134:135]
	s_add_i32 m0, s36, 0xe000
	s_nop 0
	global_load_lds_dwordx4 v[140:141], off
	s_waitcnt vmcnt(8)
	s_waitcnt lgkmcnt(0)
	s_barrier
	s_waitcnt lgkmcnt(0)
	v_mfma_f32_16x16x32_bf16 v[126:129], v[148:151], v[180:183], v[126:129]
	v_mfma_f32_16x16x32_bf16 v[122:125], v[152:155], v[180:183], v[122:125]
	v_mfma_f32_16x16x32_bf16 v[110:113], v[148:151], v[188:191], v[110:113]
	v_mfma_f32_16x16x32_bf16 v[106:109], v[152:155], v[188:191], v[106:109]
	v_mfma_f32_16x16x32_bf16 v[94:97], v[148:151], v[196:199], v[94:97]
	v_mfma_f32_16x16x32_bf16 v[90:93], v[152:155], v[196:199], v[90:93]
	v_mfma_f32_16x16x32_bf16 v[78:81], v[148:151], v[204:207], v[78:81]
	v_mfma_f32_16x16x32_bf16 v[74:77], v[152:155], v[204:207], v[74:77]
	v_mfma_f32_16x16x32_bf16 v[126:129], v[156:159], v[184:187], v[126:129]
	v_mfma_f32_16x16x32_bf16 v[122:125], v[160:163], v[184:187], v[122:125]
	v_mfma_f32_16x16x32_bf16 v[110:113], v[156:159], v[192:195], v[110:113]
	v_mfma_f32_16x16x32_bf16 v[106:109], v[160:163], v[192:195], v[106:109]
	v_mfma_f32_16x16x32_bf16 v[94:97], v[156:159], v[200:203], v[94:97]
	v_mfma_f32_16x16x32_bf16 v[90:93], v[160:163], v[200:203], v[90:93]
	v_mfma_f32_16x16x32_bf16 v[78:81], v[156:159], v[208:211], v[78:81]
	v_mfma_f32_16x16x32_bf16 v[74:77], v[160:163], v[208:211], v[74:77]
	v_mfma_f32_16x16x32_bf16 v[118:121], v[164:167], v[180:183], v[118:121]
	v_mfma_f32_16x16x32_bf16 v[114:117], v[168:171], v[180:183], v[114:117]
	v_mfma_f32_16x16x32_bf16 v[102:105], v[164:167], v[188:191], v[102:105]
	v_mfma_f32_16x16x32_bf16 v[98:101], v[168:171], v[188:191], v[98:101]
	v_mfma_f32_16x16x32_bf16 v[86:89], v[164:167], v[196:199], v[86:89]
	v_mfma_f32_16x16x32_bf16 v[82:85], v[168:171], v[196:199], v[82:85]
	v_mfma_f32_16x16x32_bf16 v[70:73], v[164:167], v[204:207], v[70:73]
	v_mfma_f32_16x16x32_bf16 v[66:69], v[168:171], v[204:207], v[66:69]
	v_mfma_f32_16x16x32_bf16 v[118:121], v[172:175], v[184:187], v[118:121]
	v_mfma_f32_16x16x32_bf16 v[114:117], v[176:179], v[184:187], v[114:117]
	v_mfma_f32_16x16x32_bf16 v[102:105], v[172:175], v[192:195], v[102:105]
	v_mfma_f32_16x16x32_bf16 v[98:101], v[176:179], v[192:195], v[98:101]
	v_mfma_f32_16x16x32_bf16 v[86:89], v[172:175], v[200:203], v[86:89]
	v_mfma_f32_16x16x32_bf16 v[82:85], v[176:179], v[200:203], v[82:85]
	v_mfma_f32_16x16x32_bf16 v[70:73], v[172:175], v[208:211], v[70:73]
	v_mfma_f32_16x16x32_bf16 v[66:69], v[176:179], v[208:211], v[66:69]
	s_barrier
	s_add_i32 s2, s83, s18
	v_lshl_add_u64 v[140:141], s[60:61], 0, v[132:133]
	s_mov_b32 m0, s2
	ds_read_b128 v[180:183], v145 offset:16384
	ds_read_b128 v[184:187], v145 offset:17408
	ds_read_b128 v[188:191], v145 offset:18432
	ds_read_b128 v[192:195], v145 offset:19456
	ds_read_b128 v[196:199], v145 offset:20480
	ds_read_b128 v[200:203], v145 offset:21504
	ds_read_b128 v[204:207], v145 offset:22528
	ds_read_b128 v[208:211], v145 offset:23552
	global_load_lds_dwordx4 v[140:141], off
	v_lshl_add_u64 v[212:213], s[60:61], 0, v[136:137]
	s_add_i32 m0, s2, 0x2000
	s_add_i32 s2, s84, s18
	global_load_lds_dwordx4 v[212:213], off
	v_lshl_add_u64 v[140:141], v[140:141], 0, s[10:11]
	s_mov_b32 m0, s2
	s_nop 0
	global_load_lds_dwordx4 v[140:141], off
	v_lshl_add_u64 v[140:141], v[212:213], 0, s[10:11]
	s_add_i32 m0, s2, 0x2000
	v_lshl_add_u64 v[212:213], s[4:5], 0, v[134:135]
	global_load_lds_dwordx4 v[140:141], off
	v_lshl_add_u64 v[140:141], s[4:5], 0, v[130:131]
	s_mov_b32 m0, s36
	s_nop 0
	global_load_lds_dwordx4 v[140:141], off
	s_mov_b32 m0, s37
	s_nop 0
	global_load_lds_dwordx4 v[212:213], off
	s_waitcnt vmcnt(8)
	s_waitcnt lgkmcnt(0)
	s_barrier
	s_waitcnt lgkmcnt(0)
	v_mfma_f32_16x16x32_bf16 v[62:65], v[148:151], v[180:183], v[62:65]
	v_mfma_f32_16x16x32_bf16 v[58:61], v[152:155], v[180:183], v[58:61]
	v_mfma_f32_16x16x32_bf16 v[46:49], v[148:151], v[188:191], v[46:49]
	v_mfma_f32_16x16x32_bf16 v[42:45], v[152:155], v[188:191], v[42:45]
	v_mfma_f32_16x16x32_bf16 v[30:33], v[148:151], v[196:199], v[30:33]
	v_mfma_f32_16x16x32_bf16 v[26:29], v[152:155], v[196:199], v[26:29]
	v_mfma_f32_16x16x32_bf16 v[14:17], v[148:151], v[204:207], v[14:17]
	v_mfma_f32_16x16x32_bf16 v[10:13], v[152:155], v[204:207], v[10:13]
	v_mfma_f32_16x16x32_bf16 v[62:65], v[156:159], v[184:187], v[62:65]
	v_mfma_f32_16x16x32_bf16 v[58:61], v[160:163], v[184:187], v[58:61]
	v_mfma_f32_16x16x32_bf16 v[46:49], v[156:159], v[192:195], v[46:49]
	v_mfma_f32_16x16x32_bf16 v[42:45], v[160:163], v[192:195], v[42:45]
	v_mfma_f32_16x16x32_bf16 v[30:33], v[156:159], v[200:203], v[30:33]
	v_mfma_f32_16x16x32_bf16 v[26:29], v[160:163], v[200:203], v[26:29]
	v_mfma_f32_16x16x32_bf16 v[14:17], v[156:159], v[208:211], v[14:17]
	v_mfma_f32_16x16x32_bf16 v[10:13], v[160:163], v[208:211], v[10:13]
	v_mfma_f32_16x16x32_bf16 v[54:57], v[164:167], v[180:183], v[54:57]
	v_mfma_f32_16x16x32_bf16 v[50:53], v[168:171], v[180:183], v[50:53]
	v_mfma_f32_16x16x32_bf16 v[38:41], v[164:167], v[188:191], v[38:41]
	v_mfma_f32_16x16x32_bf16 v[34:37], v[168:171], v[188:191], v[34:37]
	v_mfma_f32_16x16x32_bf16 v[22:25], v[164:167], v[196:199], v[22:25]
	v_mfma_f32_16x16x32_bf16 v[18:21], v[168:171], v[196:199], v[18:21]
	v_mfma_f32_16x16x32_bf16 v[6:9], v[164:167], v[204:207], v[6:9]
	v_mfma_f32_16x16x32_bf16 v[2:5], v[168:171], v[204:207], v[2:5]
	v_mfma_f32_16x16x32_bf16 v[54:57], v[172:175], v[184:187], v[54:57]
	v_mfma_f32_16x16x32_bf16 v[50:53], v[176:179], v[184:187], v[50:53]
	v_mfma_f32_16x16x32_bf16 v[38:41], v[172:175], v[192:195], v[38:41]
	v_mfma_f32_16x16x32_bf16 v[34:37], v[176:179], v[192:195], v[34:37]
	v_mfma_f32_16x16x32_bf16 v[22:25], v[172:175], v[200:203], v[22:25]
	v_mfma_f32_16x16x32_bf16 v[18:21], v[176:179], v[200:203], v[18:21]
	v_mfma_f32_16x16x32_bf16 v[6:9], v[172:175], v[208:211], v[6:9]
	v_mfma_f32_16x16x32_bf16 v[2:5], v[176:179], v[208:211], v[2:5]
	s_barrier
	s_add_i32 s20, 0, 0x18000
	v_add_u32_e32 v147, s20, v1
	s_add_i32 s21, 0, 0x1c000
	ds_read_b128 v[148:151], v147
	ds_read_b128 v[152:155], v147 offset:256
	ds_read_b128 v[156:159], v147 offset:8192
	ds_read_b128 v[160:163], v147 offset:8448
	v_add_u32_e32 v147, s21, v1
	ds_read_b128 v[164:167], v147
	ds_read_b128 v[168:171], v147 offset:256
	ds_read_b128 v[172:175], v147 offset:8192
	ds_read_b128 v[176:179], v147 offset:8448
	s_add_u32 s2, s4, 0x104000
	s_addc_u32 s3, s5, 0
	s_mov_b32 m0, s41
	v_lshl_add_u64 v[214:215], s[2:3], 0, v[130:131]
	ds_read_b128 v[180:183], v145 offset:32768
	ds_read_b128 v[184:187], v145 offset:33792
	ds_read_b128 v[188:191], v145 offset:34816
	ds_read_b128 v[192:195], v145 offset:35840
	ds_read_b128 v[196:199], v145 offset:36864
	ds_read_b128 v[200:203], v145 offset:37888
	ds_read_b128 v[204:207], v145 offset:38912
	ds_read_b128 v[208:211], v145 offset:39936
	global_load_lds_dwordx4 v[214:215], off
	v_lshl_add_u64 v[214:215], s[2:3], 0, v[134:135]
	s_mov_b32 m0, s76
	s_nop 0
	global_load_lds_dwordx4 v[214:215], off
	s_waitcnt vmcnt(8)
	s_waitcnt lgkmcnt(0)
	s_barrier
	s_waitcnt lgkmcnt(0)
	v_mfma_f32_16x16x32_bf16 v[126:129], v[148:151], v[180:183], v[126:129]
	v_mfma_f32_16x16x32_bf16 v[122:125], v[152:155], v[180:183], v[122:125]
	v_mfma_f32_16x16x32_bf16 v[110:113], v[148:151], v[188:191], v[110:113]
	v_mfma_f32_16x16x32_bf16 v[106:109], v[152:155], v[188:191], v[106:109]
	v_mfma_f32_16x16x32_bf16 v[94:97], v[148:151], v[196:199], v[94:97]
	v_mfma_f32_16x16x32_bf16 v[90:93], v[152:155], v[196:199], v[90:93]
	v_mfma_f32_16x16x32_bf16 v[78:81], v[148:151], v[204:207], v[78:81]
	v_mfma_f32_16x16x32_bf16 v[74:77], v[152:155], v[204:207], v[74:77]
	v_mfma_f32_16x16x32_bf16 v[126:129], v[156:159], v[184:187], v[126:129]
	v_mfma_f32_16x16x32_bf16 v[122:125], v[160:163], v[184:187], v[122:125]
	v_mfma_f32_16x16x32_bf16 v[110:113], v[156:159], v[192:195], v[110:113]
	v_mfma_f32_16x16x32_bf16 v[106:109], v[160:163], v[192:195], v[106:109]
	v_mfma_f32_16x16x32_bf16 v[94:97], v[156:159], v[200:203], v[94:97]
	v_mfma_f32_16x16x32_bf16 v[90:93], v[160:163], v[200:203], v[90:93]
	v_mfma_f32_16x16x32_bf16 v[78:81], v[156:159], v[208:211], v[78:81]
	v_mfma_f32_16x16x32_bf16 v[74:77], v[160:163], v[208:211], v[74:77]
	v_mfma_f32_16x16x32_bf16 v[118:121], v[164:167], v[180:183], v[118:121]
	v_mfma_f32_16x16x32_bf16 v[114:117], v[168:171], v[180:183], v[114:117]
	v_mfma_f32_16x16x32_bf16 v[102:105], v[164:167], v[188:191], v[102:105]
	v_mfma_f32_16x16x32_bf16 v[98:101], v[168:171], v[188:191], v[98:101]
	v_mfma_f32_16x16x32_bf16 v[86:89], v[164:167], v[196:199], v[86:89]
	v_mfma_f32_16x16x32_bf16 v[82:85], v[168:171], v[196:199], v[82:85]
	v_mfma_f32_16x16x32_bf16 v[70:73], v[164:167], v[204:207], v[70:73]
	v_mfma_f32_16x16x32_bf16 v[66:69], v[168:171], v[204:207], v[66:69]
	v_mfma_f32_16x16x32_bf16 v[118:121], v[172:175], v[184:187], v[118:121]
	v_mfma_f32_16x16x32_bf16 v[114:117], v[176:179], v[184:187], v[114:117]
	v_mfma_f32_16x16x32_bf16 v[102:105], v[172:175], v[192:195], v[102:105]
	v_mfma_f32_16x16x32_bf16 v[98:101], v[176:179], v[192:195], v[98:101]
	v_mfma_f32_16x16x32_bf16 v[86:89], v[172:175], v[200:203], v[86:89]
	v_mfma_f32_16x16x32_bf16 v[82:85], v[176:179], v[200:203], v[82:85]
	v_mfma_f32_16x16x32_bf16 v[70:73], v[172:175], v[208:211], v[70:73]
	v_mfma_f32_16x16x32_bf16 v[66:69], v[176:179], v[208:211], v[66:69]
	s_barrier
	s_add_i32 s2, s20, s18
	v_lshl_add_u64 v[214:215], s[62:63], 0, v[132:133]
	s_mov_b32 m0, s2
	ds_read_b128 v[180:183], v145 offset:49152
	ds_read_b128 v[184:187], v145 offset:50176
	ds_read_b128 v[188:191], v145 offset:51200
	ds_read_b128 v[192:195], v145 offset:52224
	ds_read_b128 v[196:199], v145 offset:53248
	ds_read_b128 v[200:203], v145 offset:54272
	ds_read_b128 v[204:207], v145 offset:55296
	ds_read_b128 v[208:211], v145 offset:56320
	global_load_lds_dwordx4 v[214:215], off
	s_add_i32 m0, s2, 0x2000
	s_add_u32 s2, s60, 0x209000
	v_lshl_add_u64 v[214:215], s[62:63], 0, v[136:137]
	s_addc_u32 s3, s61, 0
	s_add_i32 s4, s21, s18
	global_load_lds_dwordx4 v[214:215], off
	v_lshl_add_u64 v[214:215], s[2:3], 0, v[132:133]
	s_mov_b32 m0, s4
	v_lshl_add_u64 v[140:141], v[140:141], 0, s[14:15]
	global_load_lds_dwordx4 v[214:215], off
	v_lshl_add_u64 v[214:215], s[2:3], 0, v[136:137]
	s_add_i32 m0, s4, 0x2000
	s_nop 0
	global_load_lds_dwordx4 v[214:215], off
	s_mov_b32 m0, s77
	s_nop 0
	global_load_lds_dwordx4 v[140:141], off
	v_lshl_add_u64 v[140:141], v[212:213], 0, s[14:15]
	s_mov_b32 m0, s78
	s_nop 0
	global_load_lds_dwordx4 v[140:141], off
	s_waitcnt vmcnt(8)
	s_waitcnt lgkmcnt(0)
	s_barrier
	s_waitcnt lgkmcnt(0)
	v_mfma_f32_16x16x32_bf16 v[62:65], v[148:151], v[180:183], v[62:65]
	v_mfma_f32_16x16x32_bf16 v[58:61], v[152:155], v[180:183], v[58:61]
	v_mfma_f32_16x16x32_bf16 v[46:49], v[148:151], v[188:191], v[46:49]
	v_mfma_f32_16x16x32_bf16 v[42:45], v[152:155], v[188:191], v[42:45]
	v_mfma_f32_16x16x32_bf16 v[30:33], v[148:151], v[196:199], v[30:33]
	v_mfma_f32_16x16x32_bf16 v[26:29], v[152:155], v[196:199], v[26:29]
	v_mfma_f32_16x16x32_bf16 v[14:17], v[148:151], v[204:207], v[14:17]
	v_mfma_f32_16x16x32_bf16 v[10:13], v[152:155], v[204:207], v[10:13]
	v_mfma_f32_16x16x32_bf16 v[62:65], v[156:159], v[184:187], v[62:65]
	v_mfma_f32_16x16x32_bf16 v[58:61], v[160:163], v[184:187], v[58:61]
	v_mfma_f32_16x16x32_bf16 v[46:49], v[156:159], v[192:195], v[46:49]
	v_mfma_f32_16x16x32_bf16 v[42:45], v[160:163], v[192:195], v[42:45]
	v_mfma_f32_16x16x32_bf16 v[30:33], v[156:159], v[200:203], v[30:33]
	v_mfma_f32_16x16x32_bf16 v[26:29], v[160:163], v[200:203], v[26:29]
	v_mfma_f32_16x16x32_bf16 v[14:17], v[156:159], v[208:211], v[14:17]
	v_mfma_f32_16x16x32_bf16 v[10:13], v[160:163], v[208:211], v[10:13]
	v_mfma_f32_16x16x32_bf16 v[54:57], v[164:167], v[180:183], v[54:57]
	v_mfma_f32_16x16x32_bf16 v[50:53], v[168:171], v[180:183], v[50:53]
	v_mfma_f32_16x16x32_bf16 v[38:41], v[164:167], v[188:191], v[38:41]
	v_mfma_f32_16x16x32_bf16 v[34:37], v[168:171], v[188:191], v[34:37]
	v_mfma_f32_16x16x32_bf16 v[22:25], v[164:167], v[196:199], v[22:25]
	v_mfma_f32_16x16x32_bf16 v[18:21], v[168:171], v[196:199], v[18:21]
	v_mfma_f32_16x16x32_bf16 v[6:9], v[164:167], v[204:207], v[6:9]
	v_mfma_f32_16x16x32_bf16 v[2:5], v[168:171], v[204:207], v[2:5]
	v_mfma_f32_16x16x32_bf16 v[54:57], v[172:175], v[184:187], v[54:57]
	v_mfma_f32_16x16x32_bf16 v[50:53], v[176:179], v[184:187], v[50:53]
	v_mfma_f32_16x16x32_bf16 v[38:41], v[172:175], v[192:195], v[38:41]
	v_mfma_f32_16x16x32_bf16 v[34:37], v[176:179], v[192:195], v[34:37]
	v_mfma_f32_16x16x32_bf16 v[22:25], v[172:175], v[200:203], v[22:25]
	v_mfma_f32_16x16x32_bf16 v[18:21], v[176:179], v[200:203], v[18:21]
	v_mfma_f32_16x16x32_bf16 v[6:9], v[172:175], v[208:211], v[6:9]
	v_mfma_f32_16x16x32_bf16 v[2:5], v[176:179], v[208:211], v[2:5]
	s_barrier
	s_add_i32 s2, s90, 2
	s_cmp_gt_u32 s90, 61
	s_cbranch_scc1 .LBB0_802
	s_mov_b32 s90, s2
	s_branch .LBB0_767

.LBB0_894:
	s_add_u32 s76, s50, 0x114000
	s_addc_u32 s77, s51, 0
	s_and_b32 s18, s12, 3
	s_lshl_b32 s15, s3, 13
	s_lshl_b32 s22, s18, 9
	s_add_u32 s12, s40, 0x88800
	s_addc_u32 s13, s41, 0
	s_add_i32 m0, s33, 0x18000
	v_lshl_add_u64 v[6:7], s[12:13], 0, v[138:139]
	s_waitcnt vmcnt(2)
	s_barrier
	global_load_lds_dwordx4 v[6:7], off
	v_lshl_add_u64 v[6:7], s[12:13], 0, v[142:143]
	s_add_i32 m0, s33, 0x1a000
	s_mov_b64 s[12:13], 0x80
	s_add_i32 s78, s33, 0x8000
	s_add_i32 s79, s33, 0xa000
	global_load_lds_dwordx4 v[6:7], off
	v_lshl_add_u64 v[2:3], v[2:3], 0, s[12:13]
	s_mov_b32 m0, s78
	s_add_u32 s20, s40, 0x89000
	global_load_lds_dwordx4 v[2:3], off
	v_lshl_add_u64 v[2:3], v[4:5], 0, s[12:13]
	s_mov_b32 m0, s79
	s_addc_u32 s21, s41, 0
	global_load_lds_dwordx4 v[2:3], off
	s_add_i32 m0, s33, 0x1c000
	v_lshl_add_u64 v[2:3], s[20:21], 0, v[138:139]
	global_load_lds_dwordx4 v[2:3], off
	v_lshl_add_u64 v[2:3], s[20:21], 0, v[142:143]
	s_add_i32 m0, s33, 0x1e000
	v_and_b32_e32 v1, 15, v0
	global_load_lds_dwordx4 v[2:3], off
	v_bfe_u32 v2, v0, 4, 2
	v_lshlrev_b32_e32 v3, 4, v2
	v_lshl_or_b32 v3, v1, 6, v3
	v_lshlrev_b32_e32 v4, 2, v0
	v_lshlrev_b32_e32 v2, 11, v2
	v_lshlrev_b32_e32 v1, 4, v1
	v_and_b32_e32 v4, 32, v4
	v_or3_b32 v182, s22, v1, v2
	s_cmpk_lt_u32 s14, 0x100
	v_and_b32_e32 v1, 3, v0
	v_and_b32_e32 v2, 60, v0
	v_bfe_u32 v0, v0, 2, 4
	v_readlane_b32 s20, v249, 2
	v_bitop3_b32 v16, v3, s15, v4 bitop3:0xde
	s_cselect_b64 s[14:15], -1, 0
	v_lshl_or_b32 v0, s3, 6, v0
	s_lshl_b32 s3, s20, 2
	s_waitcnt vmcnt(6)
	v_lshlrev_b32_e32 v3, 3, v1
	v_lshl_or_b32 v184, v1, 6, v2
	v_or_b32_e32 v2, 16, v0
	v_or_b32_e32 v4, 32, v0
	v_or_b32_e32 v6, 48, v0
	v_add_u32_e32 v8, 0x80, v0
	v_add_u32_e32 v10, 0x90, v0
	v_add_u32_e32 v12, 0xa0, v0
	v_add_u32_e32 v14, 0xb0, v0
	s_and_b32 s84, s3, 12
	s_ashr_i32 s3, s20, 6
	v_lshl_or_b32 v183, s18, 5, v3
	v_ashrrev_i32_e32 v1, 31, v0
	v_ashrrev_i32_e32 v3, 31, v2
	v_ashrrev_i32_e32 v5, 31, v4
	v_ashrrev_i32_e32 v7, 31, v6
	v_ashrrev_i32_e32 v9, 31, v8
	v_ashrrev_i32_e32 v11, 31, v10
	v_ashrrev_i32_e32 v13, 31, v12
	v_ashrrev_i32_e32 v15, 31, v14
	v_readlane_b32 s21, v249, 3
	s_add_i32 s84, s84, s3
	s_movk_i32 s3, 0x2080
	v_lshlrev_b64 v[144:145], 14, v[0:1]
	v_lshlrev_b64 v[146:147], 14, v[2:3]
	v_lshlrev_b64 v[148:149], 14, v[4:5]
	v_lshlrev_b64 v[150:151], 14, v[6:7]
	v_lshlrev_b64 v[152:153], 14, v[8:9]
	v_lshlrev_b64 v[154:155], 14, v[10:11]
	v_lshlrev_b64 v[156:157], 14, v[12:13]
	v_lshlrev_b64 v[158:159], 14, v[14:15]
	s_ashr_i32 s80, s92, 31
	s_ashr_i32 s81, s20, 31
	s_and_b32 s82, s20, 4
	s_bfe_u32 s83, s20, 0x30003
	v_mad_i64_i32 v[160:161], s[20:21], v0, s3, 0
	v_mad_i64_i32 v[162:163], s[20:21], v2, s3, 0
	v_mad_i64_i32 v[164:165], s[20:21], v4, s3, 0
	v_mad_i64_i32 v[166:167], s[20:21], v6, s3, 0
	v_mad_i64_i32 v[168:169], s[20:21], v8, s3, 0
	v_mad_i64_i32 v[170:171], s[20:21], v10, s3, 0
	v_mad_i64_i32 v[172:173], s[20:21], v12, s3, 0
	v_mad_i64_i32 v[174:175], s[20:21], v14, s3, 0
	v_mov_b32_e32 v186, s2
	s_movk_i32 s18, 0x61
	s_add_i32 s36, 0, 0x10000
	s_add_i32 s37, 0, 0x14000
	v_add_u32_e32 v185, 0, v16
	v_mov_b64_e32 v[176:177], 0x2ff
	s_barrier
	v_readfirstlane_b32 s98, v0
	s_nop 3
	s_and_b32 s98, s98, 0x3ff
	s_cmp_ge_u32 s98, 0x100
	s_cbranch_scc0 .Lprio_done3
	s_setprio 1
.Lprio_done3:
	s_branch .LBB0_897
.LBB0_895:
	s_mov_b64 s[2:3], 0

.LBB0_933:
	s_lshl_b32 s2, s88, 7
	s_add_u32 s26, s34, s2
	s_addc_u32 s27, s35, 0
	s_add_u32 s46, s26, 0x100
	s_addc_u32 s47, s27, 0
	s_and_b64 s[2:3], s[44:45], exec
	v_add_u32_e32 v187, s36, v182
	s_mul_i32 s2, s88, 0x88800
	ds_read_b128 v[128:131], v187
	ds_read_b128 v[132:135], v187 offset:256
	ds_read_b128 v[178:181], v187 offset:8192
	ds_read_b128 v[188:191], v187 offset:8448
	v_add_u32_e32 v187, s37, v182
	s_cselect_b32 s51, s47, s23
	s_cselect_b32 s50, s46, s22
	s_add_u32 s2, s40, s2
	ds_read_b128 v[192:195], v187
	ds_read_b128 v[196:199], v187 offset:256
	ds_read_b128 v[200:203], v187 offset:8192
	ds_read_b128 v[204:207], v187 offset:8448
	s_addc_u32 s3, s41, 0
	s_add_u32 s46, s2, 0x111000
	s_addc_u32 s47, s3, 0
	s_and_b64 s[2:3], s[44:45], exec
	s_cselect_b32 s44, s46, s87
	s_cselect_b32 s45, s47, s21
	s_add_u32 s46, s44, 0x88800
	s_addc_u32 s47, s45, 0
	s_add_u32 s2, s26, 0x404080
	s_addc_u32 s3, s27, 0
	v_lshl_add_u64 v[240:241], s[2:3], 0, v[136:137]
	s_add_i32 m0, s33, 0xc000
	ds_read_b128 v[208:211], v185
	ds_read_b128 v[212:215], v185 offset:1024
	ds_read_b128 v[216:219], v185 offset:2048
	ds_read_b128 v[220:223], v185 offset:3072
	ds_read_b128 v[224:227], v185 offset:4096
	ds_read_b128 v[228:231], v185 offset:5120
	ds_read_b128 v[232:235], v185 offset:6144
	ds_read_b128 v[236:239], v185 offset:7168
	global_load_lds_dwordx4 v[240:241], off
	v_lshl_add_u64 v[240:241], s[2:3], 0, v[140:141]
	s_add_i32 m0, s33, 0xe000
	s_nop 0
	global_load_lds_dwordx4 v[240:241], off
	s_waitcnt vmcnt(8)
	s_waitcnt lgkmcnt(0)
	s_barrier
	s_waitcnt lgkmcnt(0)
	v_mfma_f32_16x16x32_bf16 v[124:127], v[128:131], v[208:211], v[124:127]
	v_mfma_f32_16x16x32_bf16 v[120:123], v[132:135], v[208:211], v[120:123]
	v_mfma_f32_16x16x32_bf16 v[108:111], v[128:131], v[216:219], v[108:111]
	v_mfma_f32_16x16x32_bf16 v[104:107], v[132:135], v[216:219], v[104:107]
	v_mfma_f32_16x16x32_bf16 v[92:95], v[128:131], v[224:227], v[92:95]
	v_mfma_f32_16x16x32_bf16 v[88:91], v[132:135], v[224:227], v[88:91]
	v_mfma_f32_16x16x32_bf16 v[76:79], v[128:131], v[232:235], v[76:79]
	v_mfma_f32_16x16x32_bf16 v[72:75], v[132:135], v[232:235], v[72:75]
	v_mfma_f32_16x16x32_bf16 v[124:127], v[178:181], v[212:215], v[124:127]
	v_mfma_f32_16x16x32_bf16 v[120:123], v[188:191], v[212:215], v[120:123]
	v_mfma_f32_16x16x32_bf16 v[108:111], v[178:181], v[220:223], v[108:111]
	v_mfma_f32_16x16x32_bf16 v[104:107], v[188:191], v[220:223], v[104:107]
	v_mfma_f32_16x16x32_bf16 v[92:95], v[178:181], v[228:231], v[92:95]
	v_mfma_f32_16x16x32_bf16 v[88:91], v[188:191], v[228:231], v[88:91]
	v_mfma_f32_16x16x32_bf16 v[76:79], v[178:181], v[236:239], v[76:79]
	v_mfma_f32_16x16x32_bf16 v[72:75], v[188:191], v[236:239], v[72:75]
	v_mfma_f32_16x16x32_bf16 v[116:119], v[192:195], v[208:211], v[116:119]
	v_mfma_f32_16x16x32_bf16 v[112:115], v[196:199], v[208:211], v[112:115]
	v_mfma_f32_16x16x32_bf16 v[100:103], v[192:195], v[216:219], v[100:103]
	v_mfma_f32_16x16x32_bf16 v[96:99], v[196:199], v[216:219], v[96:99]
	v_mfma_f32_16x16x32_bf16 v[84:87], v[192:195], v[224:227], v[84:87]
	v_mfma_f32_16x16x32_bf16 v[80:83], v[196:199], v[224:227], v[80:83]
	v_mfma_f32_16x16x32_bf16 v[68:71], v[192:195], v[232:235], v[68:71]
	v_mfma_f32_16x16x32_bf16 v[64:67], v[196:199], v[232:235], v[64:67]
	v_mfma_f32_16x16x32_bf16 v[116:119], v[200:203], v[212:215], v[116:119]
	v_mfma_f32_16x16x32_bf16 v[112:115], v[204:207], v[212:215], v[112:115]
	v_mfma_f32_16x16x32_bf16 v[100:103], v[200:203], v[220:223], v[100:103]
	v_mfma_f32_16x16x32_bf16 v[96:99], v[204:207], v[220:223], v[96:99]
	v_mfma_f32_16x16x32_bf16 v[84:87], v[200:203], v[228:231], v[84:87]
	v_mfma_f32_16x16x32_bf16 v[80:83], v[204:207], v[228:231], v[80:83]
	v_mfma_f32_16x16x32_bf16 v[68:71], v[200:203], v[236:239], v[68:71]
	v_mfma_f32_16x16x32_bf16 v[64:67], v[204:207], v[236:239], v[64:67]
	s_barrier
	s_add_i32 s2, s36, s31
	v_lshl_add_u64 v[240:241], s[44:45], 0, v[138:139]
	s_mov_b32 m0, s2
	ds_read_b128 v[208:211], v185 offset:16384
	ds_read_b128 v[212:215], v185 offset:17408
	ds_read_b128 v[216:219], v185 offset:18432
	ds_read_b128 v[220:223], v185 offset:19456
	ds_read_b128 v[224:227], v185 offset:20480
	ds_read_b128 v[228:231], v185 offset:21504
	ds_read_b128 v[232:235], v185 offset:22528
	ds_read_b128 v[236:239], v185 offset:23552
	global_load_lds_dwordx4 v[240:241], off
	v_lshl_add_u64 v[242:243], s[44:45], 0, v[142:143]
	s_add_i32 m0, s2, 0x2000
	s_add_i32 s2, s37, s31
	global_load_lds_dwordx4 v[242:243], off
	v_lshl_add_u64 v[240:241], v[240:241], 0, s[4:5]
	s_mov_b32 m0, s2
	s_nop 0
	global_load_lds_dwordx4 v[240:241], off
	v_lshl_add_u64 v[240:241], v[242:243], 0, s[4:5]
	s_add_i32 m0, s2, 0x2000
	v_lshl_add_u64 v[242:243], s[50:51], 0, v[140:141]
	global_load_lds_dwordx4 v[240:241], off
	v_lshl_add_u64 v[240:241], s[50:51], 0, v[136:137]
	s_mov_b32 m0, s33
	s_nop 0
	global_load_lds_dwordx4 v[240:241], off
	s_mov_b32 m0, s72
	s_nop 0
	global_load_lds_dwordx4 v[242:243], off
	s_waitcnt vmcnt(8)
	s_waitcnt lgkmcnt(0)
	s_barrier
	s_waitcnt lgkmcnt(0)
	v_mfma_f32_16x16x32_bf16 v[60:63], v[128:131], v[208:211], v[60:63]
	v_mfma_f32_16x16x32_bf16 v[56:59], v[132:135], v[208:211], v[56:59]
	v_mfma_f32_16x16x32_bf16 v[44:47], v[128:131], v[216:219], v[44:47]
	v_mfma_f32_16x16x32_bf16 v[40:43], v[132:135], v[216:219], v[40:43]
	v_mfma_f32_16x16x32_bf16 v[28:31], v[128:131], v[224:227], v[28:31]
	v_mfma_f32_16x16x32_bf16 v[24:27], v[132:135], v[224:227], v[24:27]
	v_mfma_f32_16x16x32_bf16 v[12:15], v[128:131], v[232:235], v[12:15]
	v_mfma_f32_16x16x32_bf16 v[8:11], v[132:135], v[232:235], v[8:11]
	v_mfma_f32_16x16x32_bf16 v[60:63], v[178:181], v[212:215], v[60:63]
	v_mfma_f32_16x16x32_bf16 v[56:59], v[188:191], v[212:215], v[56:59]
	v_mfma_f32_16x16x32_bf16 v[44:47], v[178:181], v[220:223], v[44:47]
	v_mfma_f32_16x16x32_bf16 v[40:43], v[188:191], v[220:223], v[40:43]
	v_mfma_f32_16x16x32_bf16 v[28:31], v[178:181], v[228:231], v[28:31]
	v_mfma_f32_16x16x32_bf16 v[24:27], v[188:191], v[228:231], v[24:27]
	v_mfma_f32_16x16x32_bf16 v[12:15], v[178:181], v[236:239], v[12:15]
	v_mfma_f32_16x16x32_bf16 v[8:11], v[188:191], v[236:239], v[8:11]
	v_mfma_f32_16x16x32_bf16 v[52:55], v[192:195], v[208:211], v[52:55]
	v_mfma_f32_16x16x32_bf16 v[48:51], v[196:199], v[208:211], v[48:51]
	v_mfma_f32_16x16x32_bf16 v[36:39], v[192:195], v[216:219], v[36:39]
	v_mfma_f32_16x16x32_bf16 v[32:35], v[196:199], v[216:219], v[32:35]
	v_mfma_f32_16x16x32_bf16 v[20:23], v[192:195], v[224:227], v[20:23]
	v_mfma_f32_16x16x32_bf16 v[16:19], v[196:199], v[224:227], v[16:19]
	v_mfma_f32_16x16x32_bf16 v[4:7], v[192:195], v[232:235], v[4:7]
	v_mfma_f32_16x16x32_bf16 v[0:3], v[196:199], v[232:235], v[0:3]
	v_mfma_f32_16x16x32_bf16 v[52:55], v[200:203], v[212:215], v[52:55]
	v_mfma_f32_16x16x32_bf16 v[48:51], v[204:207], v[212:215], v[48:51]
	v_mfma_f32_16x16x32_bf16 v[36:39], v[200:203], v[220:223], v[36:39]
	v_mfma_f32_16x16x32_bf16 v[32:35], v[204:207], v[220:223], v[32:35]
	v_mfma_f32_16x16x32_bf16 v[20:23], v[200:203], v[228:231], v[20:23]
	v_mfma_f32_16x16x32_bf16 v[16:19], v[204:207], v[228:231], v[16:19]
	v_mfma_f32_16x16x32_bf16 v[4:7], v[200:203], v[236:239], v[4:7]
	v_mfma_f32_16x16x32_bf16 v[0:3], v[204:207], v[236:239], v[0:3]
	s_barrier
	s_add_i32 s26, 0, 0x18000
	v_add_u32_e32 v187, s26, v182
	s_add_i32 s27, 0, 0x1c000
	ds_read_b128 v[128:131], v187
	ds_read_b128 v[132:135], v187 offset:256
	ds_read_b128 v[178:181], v187 offset:8192
	ds_read_b128 v[188:191], v187 offset:8448
	v_add_u32_e32 v187, s27, v182
	ds_read_b128 v[192:195], v187
	ds_read_b128 v[196:199], v187 offset:256
	ds_read_b128 v[200:203], v187 offset:8192
	ds_read_b128 v[204:207], v187 offset:8448
	s_add_u32 s2, s50, 0x404000
	s_addc_u32 s3, s51, 0
	s_mov_b32 m0, s73
	v_lshl_add_u64 v[244:245], s[2:3], 0, v[136:137]
	ds_read_b128 v[208:211], v185 offset:32768
	ds_read_b128 v[212:215], v185 offset:33792
	ds_read_b128 v[216:219], v185 offset:34816
	ds_read_b128 v[220:223], v185 offset:35840
	ds_read_b128 v[224:227], v185 offset:36864
	ds_read_b128 v[228:231], v185 offset:37888
	ds_read_b128 v[232:235], v185 offset:38912
	ds_read_b128 v[236:239], v185 offset:39936
	global_load_lds_dwordx4 v[244:245], off
	v_lshl_add_u64 v[244:245], s[2:3], 0, v[140:141]
	s_mov_b32 m0, s74
	s_nop 0
	global_load_lds_dwordx4 v[244:245], off
	s_waitcnt vmcnt(8)
	s_waitcnt lgkmcnt(0)
	s_barrier
	s_waitcnt lgkmcnt(0)
	v_mfma_f32_16x16x32_bf16 v[124:127], v[128:131], v[208:211], v[124:127]
	v_mfma_f32_16x16x32_bf16 v[120:123], v[132:135], v[208:211], v[120:123]
	v_mfma_f32_16x16x32_bf16 v[108:111], v[128:131], v[216:219], v[108:111]
	v_mfma_f32_16x16x32_bf16 v[104:107], v[132:135], v[216:219], v[104:107]
	v_mfma_f32_16x16x32_bf16 v[92:95], v[128:131], v[224:227], v[92:95]
	v_mfma_f32_16x16x32_bf16 v[88:91], v[132:135], v[224:227], v[88:91]
	v_mfma_f32_16x16x32_bf16 v[76:79], v[128:131], v[232:235], v[76:79]
	v_mfma_f32_16x16x32_bf16 v[72:75], v[132:135], v[232:235], v[72:75]
	v_mfma_f32_16x16x32_bf16 v[124:127], v[178:181], v[212:215], v[124:127]
	v_mfma_f32_16x16x32_bf16 v[120:123], v[188:191], v[212:215], v[120:123]
	v_mfma_f32_16x16x32_bf16 v[108:111], v[178:181], v[220:223], v[108:111]
	v_mfma_f32_16x16x32_bf16 v[104:107], v[188:191], v[220:223], v[104:107]
	v_mfma_f32_16x16x32_bf16 v[92:95], v[178:181], v[228:231], v[92:95]
	v_mfma_f32_16x16x32_bf16 v[88:91], v[188:191], v[228:231], v[88:91]
	v_mfma_f32_16x16x32_bf16 v[76:79], v[178:181], v[236:239], v[76:79]
	v_mfma_f32_16x16x32_bf16 v[72:75], v[188:191], v[236:239], v[72:75]
	v_mfma_f32_16x16x32_bf16 v[116:119], v[192:195], v[208:211], v[116:119]
	v_mfma_f32_16x16x32_bf16 v[112:115], v[196:199], v[208:211], v[112:115]
	v_mfma_f32_16x16x32_bf16 v[100:103], v[192:195], v[216:219], v[100:103]
	v_mfma_f32_16x16x32_bf16 v[96:99], v[196:199], v[216:219], v[96:99]
	v_mfma_f32_16x16x32_bf16 v[84:87], v[192:195], v[224:227], v[84:87]
	v_mfma_f32_16x16x32_bf16 v[80:83], v[196:199], v[224:227], v[80:83]
	v_mfma_f32_16x16x32_bf16 v[68:71], v[192:195], v[232:235], v[68:71]
	v_mfma_f32_16x16x32_bf16 v[64:67], v[196:199], v[232:235], v[64:67]
	v_mfma_f32_16x16x32_bf16 v[116:119], v[200:203], v[212:215], v[116:119]
	v_mfma_f32_16x16x32_bf16 v[112:115], v[204:207], v[212:215], v[112:115]
	v_mfma_f32_16x16x32_bf16 v[100:103], v[200:203], v[220:223], v[100:103]
	v_mfma_f32_16x16x32_bf16 v[96:99], v[204:207], v[220:223], v[96:99]
	v_mfma_f32_16x16x32_bf16 v[84:87], v[200:203], v[228:231], v[84:87]
	v_mfma_f32_16x16x32_bf16 v[80:83], v[204:207], v[228:231], v[80:83]
	v_mfma_f32_16x16x32_bf16 v[68:71], v[200:203], v[236:239], v[68:71]
	v_mfma_f32_16x16x32_bf16 v[64:67], v[204:207], v[236:239], v[64:67]
	s_barrier
	s_add_i32 s2, s26, s31
	v_lshl_add_u64 v[244:245], s[46:47], 0, v[138:139]
	s_mov_b32 m0, s2
	ds_read_b128 v[208:211], v185 offset:49152
	ds_read_b128 v[212:215], v185 offset:50176
	ds_read_b128 v[216:219], v185 offset:51200
	ds_read_b128 v[220:223], v185 offset:52224
	ds_read_b128 v[224:227], v185 offset:53248
	ds_read_b128 v[228:231], v185 offset:54272
	ds_read_b128 v[232:235], v185 offset:55296
	ds_read_b128 v[236:239], v185 offset:56320
	global_load_lds_dwordx4 v[244:245], off
	s_add_i32 m0, s2, 0x2000
	s_add_u32 s2, s44, 0x89000
	v_lshl_add_u64 v[244:245], s[46:47], 0, v[142:143]
	s_addc_u32 s3, s45, 0
	s_add_i32 s26, s27, s31
	global_load_lds_dwordx4 v[244:245], off
	v_lshl_add_u64 v[244:245], s[2:3], 0, v[138:139]
	s_mov_b32 m0, s26
	v_lshl_add_u64 v[240:241], v[240:241], 0, s[12:13]
	global_load_lds_dwordx4 v[244:245], off
	v_lshl_add_u64 v[244:245], s[2:3], 0, v[142:143]
	s_add_i32 m0, s26, 0x2000
	s_nop 0
	global_load_lds_dwordx4 v[244:245], off
	s_mov_b32 m0, s78
	s_nop 0
	global_load_lds_dwordx4 v[240:241], off
	v_lshl_add_u64 v[240:241], v[242:243], 0, s[12:13]
	s_mov_b32 m0, s79
	s_nop 0
	global_load_lds_dwordx4 v[240:241], off
	s_waitcnt vmcnt(8)
	s_waitcnt lgkmcnt(0)
	s_barrier
	s_waitcnt lgkmcnt(0)
	v_mfma_f32_16x16x32_bf16 v[60:63], v[128:131], v[208:211], v[60:63]
	v_mfma_f32_16x16x32_bf16 v[56:59], v[132:135], v[208:211], v[56:59]
	v_mfma_f32_16x16x32_bf16 v[44:47], v[128:131], v[216:219], v[44:47]
	v_mfma_f32_16x16x32_bf16 v[40:43], v[132:135], v[216:219], v[40:43]
	v_mfma_f32_16x16x32_bf16 v[28:31], v[128:131], v[224:227], v[28:31]
	v_mfma_f32_16x16x32_bf16 v[24:27], v[132:135], v[224:227], v[24:27]
	v_mfma_f32_16x16x32_bf16 v[12:15], v[128:131], v[232:235], v[12:15]
	v_mfma_f32_16x16x32_bf16 v[8:11], v[132:135], v[232:235], v[8:11]
	v_mfma_f32_16x16x32_bf16 v[60:63], v[178:181], v[212:215], v[60:63]
	v_mfma_f32_16x16x32_bf16 v[56:59], v[188:191], v[212:215], v[56:59]
	v_mfma_f32_16x16x32_bf16 v[44:47], v[178:181], v[220:223], v[44:47]
	v_mfma_f32_16x16x32_bf16 v[40:43], v[188:191], v[220:223], v[40:43]
	v_mfma_f32_16x16x32_bf16 v[28:31], v[178:181], v[228:231], v[28:31]
	v_mfma_f32_16x16x32_bf16 v[24:27], v[188:191], v[228:231], v[24:27]
	v_mfma_f32_16x16x32_bf16 v[12:15], v[178:181], v[236:239], v[12:15]
	v_mfma_f32_16x16x32_bf16 v[8:11], v[188:191], v[236:239], v[8:11]
	v_mfma_f32_16x16x32_bf16 v[52:55], v[192:195], v[208:211], v[52:55]
	v_mfma_f32_16x16x32_bf16 v[48:51], v[196:199], v[208:211], v[48:51]
	v_mfma_f32_16x16x32_bf16 v[36:39], v[192:195], v[216:219], v[36:39]
	v_mfma_f32_16x16x32_bf16 v[32:35], v[196:199], v[216:219], v[32:35]
	v_mfma_f32_16x16x32_bf16 v[20:23], v[192:195], v[224:227], v[20:23]
	v_mfma_f32_16x16x32_bf16 v[16:19], v[196:199], v[224:227], v[16:19]
	v_mfma_f32_16x16x32_bf16 v[4:7], v[192:195], v[232:235], v[4:7]
	v_mfma_f32_16x16x32_bf16 v[0:3], v[196:199], v[232:235], v[0:3]
	v_mfma_f32_16x16x32_bf16 v[52:55], v[200:203], v[212:215], v[52:55]
	v_mfma_f32_16x16x32_bf16 v[48:51], v[204:207], v[212:215], v[48:51]
	v_mfma_f32_16x16x32_bf16 v[36:39], v[200:203], v[220:223], v[36:39]
	v_mfma_f32_16x16x32_bf16 v[32:35], v[204:207], v[220:223], v[32:35]
	v_mfma_f32_16x16x32_bf16 v[20:23], v[200:203], v[228:231], v[20:23]
	v_mfma_f32_16x16x32_bf16 v[16:19], v[204:207], v[228:231], v[16:19]
	v_mfma_f32_16x16x32_bf16 v[4:7], v[200:203], v[236:239], v[4:7]
	v_mfma_f32_16x16x32_bf16 v[0:3], v[204:207], v[236:239], v[0:3]
	s_barrier
	s_add_i32 s2, s88, 2
	s_cmpk_gt_u32 s88, 0xfd
	s_cbranch_scc1 .LBB0_939
	s_mov_b32 s88, s2
	s_branch .LBB0_904
